# dwconv LayerNorm-SiLU: interleaved IEEE divisions replaced by v_rcp_f32+mul (dataflow-matched), hazard nops re-derived
# baseline (speedup 1.0000x reference)
.LBB0_501:
	s_cmpk_lt_i32 s94, 0x400
	s_cselect_b32 s89, 0, 0x4000
	s_cselect_b32 s88, s86, 0x4100
	s_add_i32 s3, s2, -15
	s_cmp_ge_i32 s3, s89
	s_cselect_b64 s[0:1], -1, 0
	s_cmp_lt_i32 s3, s88
	s_cselect_b64 s[4:5], -1, 0
	s_and_b64 s[0:1], s[0:1], s[4:5]
	s_and_b64 s[4:5], s[0:1], exec
	s_cselect_b32 s4, s3, s2
	s_ashr_i32 s5, s4, 31
	s_lshl_b64 s[4:5], s[4:5], 11
	s_add_i32 s3, s2, -14
	s_cmp_ge_i32 s3, s89
	v_lshl_add_u64 v[18:19], v[114:115], 0, s[4:5]
	s_cselect_b64 s[4:5], -1, 0
	s_cmp_lt_i32 s3, s88
	s_cselect_b64 s[6:7], -1, 0
	s_and_b64 s[6:7], s[4:5], s[6:7]
	s_and_b64 s[4:5], s[6:7], exec
	s_cselect_b32 s4, s3, s2
	s_ashr_i32 s5, s4, 31
	s_lshl_b64 s[4:5], s[4:5], 11
	s_add_i32 s3, s2, -13
	s_cmp_ge_i32 s3, s89
	global_load_dword v0, v[18:19], off
	v_lshl_add_u64 v[18:19], v[114:115], 0, s[4:5]
	s_cselect_b64 s[4:5], -1, 0
	s_cmp_lt_i32 s3, s88
	s_cselect_b64 s[8:9], -1, 0
	s_and_b64 s[12:13], s[4:5], s[8:9]
	s_and_b64 s[4:5], s[12:13], exec
	s_cselect_b32 s4, s3, s2
	s_ashr_i32 s5, s4, 31
	s_lshl_b64 s[4:5], s[4:5], 11
	s_add_i32 s3, s2, -12
	s_cmp_ge_i32 s3, s89
	v_lshl_add_u64 v[20:21], v[114:115], 0, s[4:5]
	s_cselect_b64 s[4:5], -1, 0
	s_cmp_lt_i32 s3, s88
	s_cselect_b64 s[8:9], -1, 0
	s_and_b64 s[30:31], s[4:5], s[8:9]
	s_and_b64 s[4:5], s[30:31], exec
	s_cselect_b32 s4, s3, s2
	s_ashr_i32 s5, s4, 31
	s_lshl_b64 s[4:5], s[4:5], 11
	s_add_i32 s3, s2, -11
	s_cmp_ge_i32 s3, s89
	v_lshl_add_u64 v[22:23], v[114:115], 0, s[4:5]
	s_cselect_b64 s[4:5], -1, 0
	s_cmp_lt_i32 s3, s88
	s_cselect_b64 s[8:9], -1, 0
	s_and_b64 s[36:37], s[4:5], s[8:9]
	s_and_b64 s[4:5], s[36:37], exec
	s_cselect_b32 s4, s3, s2
	s_ashr_i32 s5, s4, 31
	s_lshl_b64 s[4:5], s[4:5], 11
	s_add_i32 s3, s2, -10
	s_cmp_ge_i32 s3, s89
	global_load_dword v18, v[18:19], off
	s_mov_b32 s96, s70
	global_load_dword v21, v[20:21], off
	s_mov_b32 s97, s84
	global_load_dword v29, v[22:23], off
	v_lshl_add_u64 v[22:23], v[114:115], 0, s[4:5]
	s_cselect_b64 s[4:5], -1, 0
	s_cmp_lt_i32 s3, s88
	s_cselect_b64 s[8:9], -1, 0
	s_and_b64 s[50:51], s[4:5], s[8:9]
	s_and_b64 s[4:5], s[50:51], exec
	s_cselect_b32 s4, s3, s2
	s_ashr_i32 s5, s4, 31
	s_lshl_b64 s[4:5], s[4:5], 11
	s_add_i32 s3, s2, -9
	s_cmp_ge_i32 s3, s89
	global_load_dword v32, v[22:23], off
	v_lshl_add_u64 v[22:23], v[114:115], 0, s[4:5]
	s_cselect_b64 s[4:5], -1, 0
	s_cmp_lt_i32 s3, s88
	s_cselect_b64 s[8:9], -1, 0
	s_and_b64 s[58:59], s[4:5], s[8:9]
	s_and_b64 s[4:5], s[58:59], exec
	s_cselect_b32 s4, s3, s2
	s_ashr_i32 s5, s4, 31
	s_lshl_b64 s[4:5], s[4:5], 11
	s_add_i32 s3, s2, -8
	s_cmp_gt_i32 s2, s89
	global_load_dword v38, v[22:23], off
	v_lshl_add_u64 v[22:23], v[114:115], 0, s[4:5]
	s_cselect_b64 s[4:5], -1, 0
	s_cmp_le_i32 s2, s88
	s_cselect_b64 s[8:9], -1, 0
	s_and_b64 vcc, s[4:5], s[8:9]
	s_and_b64 s[4:5], vcc, exec
	s_cselect_b32 s4, s3, s2
	s_ashr_i32 s5, s4, 31
	s_lshl_b64 s[4:5], s[4:5], 11
	s_add_i32 s3, s2, -7
	s_cmp_ge_i32 s3, s89
	global_load_dword v43, v[22:23], off
	v_lshl_add_u64 v[22:23], v[114:115], 0, s[4:5]
	s_cselect_b64 s[4:5], -1, 0
	s_cmp_lt_i32 s3, s88
	s_cselect_b64 s[8:9], -1, 0
	s_and_b64 s[70:71], s[4:5], s[8:9]
	s_and_b64 s[4:5], s[70:71], exec
	s_cselect_b32 s4, s3, s2
	s_ashr_i32 s5, s4, 31
	s_lshl_b64 s[4:5], s[4:5], 11
	s_add_i32 s3, s2, -6
	s_cmp_ge_i32 s3, s89
	global_load_dword v119, v[22:23], off
	v_lshl_add_u64 v[22:23], v[114:115], 0, s[4:5]
	s_cselect_b64 s[4:5], -1, 0
	s_cmp_lt_i32 s3, s88
	s_cselect_b64 s[8:9], -1, 0
	s_and_b64 s[76:77], s[4:5], s[8:9]
	s_and_b64 s[4:5], s[76:77], exec
	s_cselect_b32 s4, s3, s2
	s_ashr_i32 s5, s4, 31
	s_lshl_b64 s[4:5], s[4:5], 11
	s_add_i32 s3, s2, -5
	s_cmp_ge_i32 s3, s89
	global_load_dword v134, v[22:23], off
	v_lshl_add_u64 v[22:23], v[114:115], 0, s[4:5]
	s_cselect_b64 s[4:5], -1, 0
	s_cmp_lt_i32 s3, s88
	s_cselect_b64 s[8:9], -1, 0
	s_and_b64 s[78:79], s[4:5], s[8:9]
	s_and_b64 s[4:5], s[78:79], exec
	s_cselect_b32 s4, s3, s2
	s_ashr_i32 s5, s4, 31
	s_lshl_b64 s[4:5], s[4:5], 11
	s_add_i32 s3, s2, -4
	global_load_dword v137, v[22:23], off
	v_lshl_add_u64 v[22:23], v[114:115], 0, s[4:5]
	s_and_b64 s[4:5], vcc, exec
	s_cselect_b32 s4, s3, s2
	s_ashr_i32 s5, s4, 31
	s_lshl_b64 s[4:5], s[4:5], 11
	s_add_i32 s3, s2, -3
	s_cmp_ge_i32 s3, s89
	global_load_dword v138, v[22:23], off
	v_lshl_add_u64 v[22:23], v[114:115], 0, s[4:5]
	s_cselect_b64 s[4:5], -1, 0
	s_cmp_lt_i32 s3, s88
	s_cselect_b64 s[8:9], -1, 0
	s_and_b64 s[74:75], s[4:5], s[8:9]
	s_and_b64 s[4:5], s[74:75], exec
	s_cselect_b32 s4, s3, s2
	s_ashr_i32 s5, s4, 31
	s_lshl_b64 s[4:5], s[4:5], 11
	s_add_i32 s3, s2, -2
	global_load_dword v135, v[22:23], off
	v_lshl_add_u64 v[22:23], v[114:115], 0, s[4:5]
	s_and_b64 s[4:5], vcc, exec
	s_cselect_b32 s4, s3, s2
	s_ashr_i32 s5, s4, 31
	s_lshl_b64 s[4:5], s[4:5], 11
	s_cmp_lg_u64 vcc, 0
	global_load_dword v136, v[22:23], off
	v_lshl_add_u64 v[22:23], v[114:115], 0, s[4:5]
	s_subb_u32 s4, s2, 0
	s_ashr_i32 s5, s4, 31
	s_lshl_b64 s[4:5], s[4:5], 11
	s_ashr_i32 s3, s2, 31
	global_load_dword v121, v[22:23], off
	v_lshl_add_u64 v[22:23], v[114:115], 0, s[4:5]
	s_lshl_b64 s[4:5], s[2:3], 11
	s_add_i32 s3, s2, 1
	s_cmp_ge_i32 s3, s89
	global_load_dword v49, v[22:23], off
	v_lshl_add_u64 v[22:23], v[114:115], 0, s[4:5]
	s_cselect_b64 s[4:5], -1, 0
	s_cmp_lt_i32 s3, s88
	s_cselect_b64 s[8:9], -1, 0
	s_and_b64 s[64:65], s[4:5], s[8:9]
	s_and_b64 s[4:5], s[64:65], exec
	s_cselect_b32 s4, s3, s2
	s_ashr_i32 s5, s4, 31
	s_lshl_b64 s[4:5], s[4:5], 11
	s_add_i32 s3, s2, 2
	s_cmp_ge_i32 s3, s89
	global_load_dword v47, v[22:23], off
	v_lshl_add_u64 v[22:23], v[114:115], 0, s[4:5]
	s_cselect_b64 s[4:5], -1, 0
	s_cmp_lt_i32 s3, s88
	s_cselect_b64 s[8:9], -1, 0
	s_and_b64 s[62:63], s[4:5], s[8:9]
	s_and_b64 s[4:5], s[62:63], exec
	s_cselect_b32 s4, s3, s2
	s_ashr_i32 s5, s4, 31
	s_lshl_b64 s[4:5], s[4:5], 11
	s_add_i32 s3, s2, 3
	s_cmp_ge_i32 s3, s89
	global_load_dword v48, v[22:23], off
	v_lshl_add_u64 v[22:23], v[114:115], 0, s[4:5]
	s_cselect_b64 s[4:5], -1, 0
	s_cmp_lt_i32 s3, s88
	s_cselect_b64 s[8:9], -1, 0
	s_and_b64 s[60:61], s[4:5], s[8:9]
	s_and_b64 s[4:5], s[60:61], exec
	s_cselect_b32 s4, s3, s2
	s_ashr_i32 s5, s4, 31
	s_lshl_b64 s[4:5], s[4:5], 11
	s_add_i32 s3, s2, 4
	s_cmp_ge_i32 s3, s89
	global_load_dword v46, v[22:23], off
	v_lshl_add_u64 v[22:23], v[114:115], 0, s[4:5]
	s_cselect_b64 s[4:5], -1, 0
	s_cmp_lt_i32 s3, s88
	s_cselect_b64 s[8:9], -1, 0
	s_and_b64 s[56:57], s[4:5], s[8:9]
	s_and_b64 s[4:5], s[56:57], exec
	s_cselect_b32 s4, s3, s2
	s_ashr_i32 s5, s4, 31
	s_lshl_b64 s[4:5], s[4:5], 11
	s_add_i32 s3, s2, 5
	s_cmp_ge_i32 s3, s89
	global_load_dword v44, v[22:23], off
	v_lshl_add_u64 v[22:23], v[114:115], 0, s[4:5]
	s_cselect_b64 s[4:5], -1, 0
	s_cmp_lt_i32 s3, s88
	s_cselect_b64 s[8:9], -1, 0
	s_and_b64 s[52:53], s[4:5], s[8:9]
	s_and_b64 s[4:5], s[52:53], exec
	s_cselect_b32 s4, s3, s2
	s_ashr_i32 s5, s4, 31
	s_lshl_b64 s[4:5], s[4:5], 11
	s_add_i32 s3, s2, 6
	s_cmp_ge_i32 s3, s89
	global_load_dword v42, v[22:23], off
	v_lshl_add_u64 v[22:23], v[114:115], 0, s[4:5]
	s_cselect_b64 s[4:5], -1, 0
	s_cmp_lt_i32 s3, s88
	s_cselect_b64 s[8:9], -1, 0
	s_and_b64 s[44:45], s[4:5], s[8:9]
	s_and_b64 s[4:5], s[44:45], exec
	s_cselect_b32 s4, s3, s2
	s_ashr_i32 s5, s4, 31
	s_lshl_b64 s[4:5], s[4:5], 11
	s_add_i32 s3, s2, 7
	s_cmp_ge_i32 s3, s89
	global_load_dword v39, v[22:23], off
	v_lshl_add_u64 v[22:23], v[114:115], 0, s[4:5]
	s_cselect_b64 s[4:5], -1, 0
	s_cmp_lt_i32 s3, s88
	s_cselect_b64 s[8:9], -1, 0
	s_and_b64 s[38:39], s[4:5], s[8:9]
	s_and_b64 s[4:5], s[38:39], exec
	s_cselect_b32 s4, s3, s2
	s_ashr_i32 s5, s4, 31
	s_lshl_b64 s[4:5], s[4:5], 11
	s_add_i32 s3, s2, 8
	s_cmp_ge_i32 s3, s89
	global_load_dword v36, v[22:23], off
	v_lshl_add_u64 v[22:23], v[114:115], 0, s[4:5]
	s_cselect_b64 s[4:5], -1, 0
	s_cmp_lt_i32 s3, s88
	s_cselect_b64 s[8:9], -1, 0
	s_and_b64 s[24:25], s[4:5], s[8:9]
	s_and_b64 s[4:5], s[24:25], exec
	s_cselect_b32 s4, s3, s2
	s_ashr_i32 s5, s4, 31
	s_lshl_b64 s[4:5], s[4:5], 11
	s_add_i32 s3, s2, 9
	s_cmp_ge_i32 s3, s89
	global_load_dword v33, v[22:23], off
	v_lshl_add_u64 v[22:23], v[114:115], 0, s[4:5]
	s_cselect_b64 s[4:5], -1, 0
	s_cmp_lt_i32 s3, s88
	s_cselect_b64 s[8:9], -1, 0
	s_and_b64 s[54:55], s[4:5], s[8:9]
	s_and_b64 s[4:5], s[54:55], exec
	s_cselect_b32 s4, s3, s2
	s_ashr_i32 s5, s4, 31
	s_lshl_b64 s[4:5], s[4:5], 11
	s_add_i32 s3, s2, 10
	s_cmp_ge_i32 s3, s89
	global_load_dword v40, v[22:23], off
	v_lshl_add_u64 v[22:23], v[114:115], 0, s[4:5]
	s_cselect_b64 s[4:5], -1, 0
	s_cmp_lt_i32 s3, s88
	s_cselect_b64 s[8:9], -1, 0
	s_and_b64 s[48:49], s[4:5], s[8:9]
	s_and_b64 s[4:5], s[48:49], exec
	s_cselect_b32 s4, s3, s2
	s_ashr_i32 s5, s4, 31
	s_lshl_b64 s[4:5], s[4:5], 11
	s_add_i32 s3, s2, 11
	s_cmp_ge_i32 s3, s89
	global_load_dword v41, v[22:23], off
	v_lshl_add_u64 v[22:23], v[114:115], 0, s[4:5]
	s_cselect_b64 s[4:5], -1, 0
	s_cmp_lt_i32 s3, s88
	s_cselect_b64 s[8:9], -1, 0
	s_and_b64 s[42:43], s[4:5], s[8:9]
	s_and_b64 s[4:5], s[42:43], exec
	s_cselect_b32 s4, s3, s2
	s_ashr_i32 s5, s4, 31
	s_lshl_b64 s[4:5], s[4:5], 11
	s_add_i32 s3, s2, 12
	s_cmp_ge_i32 s3, s89
	global_load_dword v37, v[22:23], off
	v_lshl_add_u64 v[22:23], v[114:115], 0, s[4:5]
	s_cselect_b64 s[4:5], -1, 0
	s_cmp_lt_i32 s3, s88
	s_cselect_b64 s[8:9], -1, 0
	s_and_b64 s[34:35], s[4:5], s[8:9]
	s_and_b64 s[4:5], s[34:35], exec
	s_cselect_b32 s4, s3, s2
	s_ashr_i32 s5, s4, 31
	s_lshl_b64 s[4:5], s[4:5], 11
	s_add_i32 s3, s2, 13
	s_cmp_ge_i32 s3, s89
	global_load_dword v35, v[22:23], off
	v_lshl_add_u64 v[22:23], v[114:115], 0, s[4:5]
	s_cselect_b64 s[4:5], -1, 0
	s_cmp_lt_i32 s3, s88
	s_cselect_b64 s[8:9], -1, 0
	s_and_b64 s[14:15], s[4:5], s[8:9]
	s_and_b64 s[4:5], s[14:15], exec
	s_cselect_b32 s4, s3, s2
	s_ashr_i32 s5, s4, 31
	s_lshl_b64 s[4:5], s[4:5], 11
	s_add_i32 s3, s2, 14
	s_cmp_ge_i32 s3, s89
	global_load_dword v30, v[22:23], off
	v_lshl_add_u64 v[22:23], v[114:115], 0, s[4:5]
	s_cselect_b64 s[4:5], -1, 0
	s_cmp_lt_i32 s3, s88
	s_cselect_b64 s[8:9], -1, 0
	s_and_b64 s[10:11], s[4:5], s[8:9]
	s_and_b64 s[4:5], s[10:11], exec
	s_cselect_b32 s4, s3, s2
	s_ashr_i32 s5, s4, 31
	s_lshl_b64 s[4:5], s[4:5], 11
	s_add_i32 s3, s2, 15
	s_cmp_ge_i32 s3, s89
	v_lshl_add_u64 v[24:25], v[114:115], 0, s[4:5]
	s_cselect_b64 s[4:5], -1, 0
	s_cmp_lt_i32 s3, s88
	s_cselect_b64 s[8:9], -1, 0
	s_and_b64 s[8:9], s[4:5], s[8:9]
	s_and_b64 s[4:5], s[8:9], exec
	s_cselect_b32 s4, s3, s2
	s_ashr_i32 s5, s4, 31
	s_lshl_b64 s[4:5], s[4:5], 11
	s_add_i32 s3, s2, 16
	s_cmp_ge_i32 s3, s89
	global_load_dword v22, v[22:23], off
	s_nop 0
	global_load_dword v20, v[24:25], off
	v_lshl_add_u64 v[24:25], v[114:115], 0, s[4:5]
	s_cselect_b64 s[4:5], -1, 0
	s_cmp_lt_i32 s3, s88
	s_cselect_b64 s[16:17], -1, 0
	s_and_b64 s[4:5], s[4:5], s[16:17]
	s_and_b64 s[16:17], s[4:5], exec
	s_cselect_b32 s16, s3, s2
	s_ashr_i32 s17, s16, 31
	s_lshl_b64 s[16:17], s[16:17], 11
	s_add_i32 s3, s2, 17
	s_cmp_ge_i32 s3, s89
	global_load_dword v19, v[24:25], off
	v_lshl_add_u64 v[24:25], v[114:115], 0, s[16:17]
	s_cselect_b64 s[16:17], -1, 0
	s_cmp_lt_i32 s3, s88
	s_cselect_b64 s[18:19], -1, 0
	s_and_b64 s[26:27], s[16:17], s[18:19]
	s_and_b64 s[16:17], s[26:27], exec
	s_cselect_b32 s16, s3, s2
	s_ashr_i32 s17, s16, 31
	s_lshl_b64 s[16:17], s[16:17], 11
	s_add_i32 s3, s2, 18
	s_cmp_ge_i32 s3, s89
	global_load_dword v27, v[24:25], off
	v_lshl_add_u64 v[24:25], v[114:115], 0, s[16:17]
	s_cselect_b64 s[16:17], -1, 0
	s_cmp_lt_i32 s3, s88
	s_cselect_b64 s[18:19], -1, 0
	s_and_b64 s[20:21], s[16:17], s[18:19]
	s_and_b64 s[16:17], s[20:21], exec
	s_cselect_b32 s16, s3, s2
	s_ashr_i32 s17, s16, 31
	s_lshl_b64 s[16:17], s[16:17], 11
	s_add_i32 s3, s2, 19
	s_cmp_ge_i32 s3, s89
	global_load_dword v31, v[24:25], off
	v_lshl_add_u64 v[24:25], v[114:115], 0, s[16:17]
	s_cselect_b64 s[16:17], -1, 0
	s_cmp_lt_i32 s3, s88
	s_cselect_b64 s[18:19], -1, 0
	s_and_b64 s[16:17], s[16:17], s[18:19]
	s_and_b64 s[18:19], s[16:17], exec
	s_cselect_b32 s18, s3, s2
	s_ashr_i32 s19, s18, 31
	s_lshl_b64 s[18:19], s[18:19], 11
	s_add_i32 s3, s2, 20
	s_cmp_ge_i32 s3, s89
	v_lshl_add_u64 v[140:141], v[114:115], 0, s[18:19]
	s_cselect_b64 s[18:19], -1, 0
	s_cmp_lt_i32 s3, s88
	s_cselect_b64 s[22:23], -1, 0
	s_and_b64 s[18:19], s[18:19], s[22:23]
	s_and_b64 s[22:23], s[18:19], exec
	s_cselect_b32 s22, s3, s2
	s_ashr_i32 s23, s22, 31
	s_lshl_b64 s[22:23], s[22:23], 11
	s_add_i32 s3, s2, 21
	s_cmp_ge_i32 s3, s89
	global_load_dword v25, v[24:25], off
	s_nop 0
	global_load_dword v23, v[140:141], off
	v_lshl_add_u64 v[140:141], v[114:115], 0, s[22:23]
	s_cselect_b64 s[22:23], -1, 0
	s_cmp_lt_i32 s3, s88
	s_cselect_b64 s[28:29], -1, 0
	s_and_b64 s[22:23], s[22:23], s[28:29]
	s_and_b64 s[28:29], s[22:23], exec
	s_cselect_b32 s28, s3, s2
	s_ashr_i32 s29, s28, 31
	s_lshl_b64 s[28:29], s[28:29], 11
	s_add_i32 s3, s2, 22
	s_cmp_ge_i32 s3, s89
	global_load_dword v24, v[140:141], off
	v_lshl_add_u64 v[140:141], v[114:115], 0, s[28:29]
	s_cselect_b64 s[28:29], -1, 0
	s_cmp_lt_i32 s3, s88
	s_cselect_b64 s[40:41], -1, 0
	s_and_b64 s[28:29], s[28:29], s[40:41]
	s_and_b64 s[40:41], s[28:29], exec
	s_cselect_b32 s40, s3, s2
	s_ashr_i32 s41, s40, 31
	s_lshl_b64 s[40:41], s[40:41], 11
	s_add_i32 s3, s2, 23
	s_cmp_ge_i32 s3, s89
	global_load_dword v26, v[140:141], off
	v_lshl_add_u64 v[140:141], v[114:115], 0, s[40:41]
	s_cselect_b64 s[40:41], -1, 0
	s_cmp_lt_i32 s3, s88
	s_cselect_b64 s[46:47], -1, 0
	s_and_b64 s[40:41], s[40:41], s[46:47]
	s_and_b64 s[46:47], s[40:41], exec
	s_cselect_b32 s46, s3, s2
	s_ashr_i32 s47, s46, 31
	s_lshl_b64 s[46:47], s[46:47], 11
	s_add_i32 s3, s2, 24
	s_cmp_ge_i32 s3, s89
	global_load_dword v28, v[140:141], off
	v_lshl_add_u64 v[140:141], v[114:115], 0, s[46:47]
	s_cselect_b64 s[46:47], -1, 0
	s_cmp_lt_i32 s3, s88
	s_cselect_b64 s[66:67], -1, 0
	s_and_b64 s[46:47], s[46:47], s[66:67]
	s_and_b64 s[66:67], s[46:47], exec
	s_cselect_b32 s66, s3, s2
	s_ashr_i32 s67, s66, 31
	s_lshl_b64 s[66:67], s[66:67], 11
	s_add_i32 s3, s2, 25
	s_cmp_ge_i32 s3, s89
	global_load_dword v34, v[140:141], off
	v_lshl_add_u64 v[140:141], v[114:115], 0, s[66:67]
	s_cselect_b64 s[66:67], -1, 0
	s_cmp_lt_i32 s3, s88
	s_cselect_b64 s[68:69], -1, 0
	s_and_b64 s[66:67], s[66:67], s[68:69]
	s_and_b64 s[68:69], s[66:67], exec
	s_cselect_b32 s68, s3, s2
	s_ashr_i32 s69, s68, 31
	s_lshl_b64 s[68:69], s[68:69], 11
	s_add_i32 s3, s2, 26
	s_cmp_ge_i32 s3, s89
	global_load_dword v45, v[140:141], off
	v_lshl_add_u64 v[140:141], v[114:115], 0, s[68:69]
	s_cselect_b64 s[68:69], -1, 0
	s_cmp_lt_i32 s3, s88
	s_cselect_b64 s[72:73], -1, 0
	s_and_b64 s[68:69], s[68:69], s[72:73]
	s_and_b64 s[72:73], s[68:69], exec
	s_cselect_b32 s72, s3, s2
	s_ashr_i32 s73, s72, 31
	s_lshl_b64 s[72:73], s[72:73], 11
	s_add_i32 s3, s2, 27
	s_cmp_ge_i32 s3, s89
	global_load_dword v118, v[140:141], off
	v_lshl_add_u64 v[140:141], v[114:115], 0, s[72:73]
	s_cselect_b64 s[72:73], -1, 0
	s_cmp_lt_i32 s3, s88
	s_cselect_b64 s[80:81], -1, 0
	s_and_b64 s[72:73], s[72:73], s[80:81]
	s_and_b64 s[80:81], s[72:73], exec
	s_cselect_b32 s80, s3, s2
	s_ashr_i32 s81, s80, 31
	s_lshl_b64 s[80:81], s[80:81], 11
	s_add_i32 s3, s2, 28
	s_cmp_ge_i32 s3, s89
	global_load_dword v120, v[140:141], off
	v_lshl_add_u64 v[140:141], v[114:115], 0, s[80:81]
	s_cselect_b64 s[80:81], -1, 0
	s_cmp_lt_i32 s3, s88
	s_cselect_b64 s[82:83], -1, 0
	s_and_b64 s[80:81], s[80:81], s[82:83]
	s_and_b64 s[82:83], s[80:81], exec
	s_cselect_b32 s82, s3, s2
	s_ashr_i32 s83, s82, 31
	s_lshl_b64 s[82:83], s[82:83], 11
	s_add_i32 s3, s2, 29
	s_cmp_ge_i32 s3, s89
	global_load_dword v133, v[140:141], off
	v_lshl_add_u64 v[140:141], v[114:115], 0, s[82:83]
	s_cselect_b64 s[82:83], -1, 0
	s_cmp_lt_i32 s3, s88
	s_cselect_b64 s[84:85], -1, 0
	s_and_b64 s[82:83], s[82:83], s[84:85]
	s_and_b64 s[84:85], s[82:83], exec
	s_cselect_b32 s84, s3, s2
	s_ashr_i32 s85, s84, 31
	s_lshl_b64 s[84:85], s[84:85], 11
	s_add_i32 s3, s2, 30
	s_cmp_ge_i32 s3, s89
	global_load_dword v139, v[140:141], off
	v_lshl_add_u64 v[140:141], v[114:115], 0, s[84:85]
	s_cselect_b64 s[84:85], -1, 0
	s_cmp_lt_i32 s3, s88
	s_cselect_b64 s[86:87], -1, 0
	s_and_b64 s[84:85], s[84:85], s[86:87]
	s_and_b64 s[86:87], s[84:85], exec
	s_cselect_b32 s86, s3, s2
	s_ashr_i32 s87, s86, 31
	s_lshl_b64 s[86:87], s[86:87], 11
	v_lshl_add_u64 v[142:143], v[114:115], 0, s[86:87]
	global_load_dword v140, v[140:141], off
	s_movk_i32 s86, 0x4000
	global_load_dword v141, v[142:143], off
	s_waitcnt vmcnt(45)
	v_lshlrev_b32_e32 v142, 16, v0
	v_and_b32_e32 v0, 0xffff0000, v0
	v_cndmask_b32_e64 v143, 0, v0, s[0:1]
	s_waitcnt vmcnt(44)
	v_lshlrev_b32_e32 v0, 16, v18
	v_cndmask_b32_e64 v144, 0, v0, s[6:7]
	v_and_b32_e32 v0, 0xffff0000, v18
	v_cndmask_b32_e64 v145, 0, v0, s[6:7]
	s_waitcnt vmcnt(43)
	v_lshlrev_b32_e32 v0, 16, v21
	v_cndmask_b32_e64 v146, 0, v0, s[12:13]
	v_and_b32_e32 v0, 0xffff0000, v21
	v_cndmask_b32_e64 v147, 0, v0, s[12:13]
	s_waitcnt vmcnt(42)
	v_lshlrev_b32_e32 v0, 16, v29
	v_cndmask_b32_e64 v148, 0, v0, s[30:31]
	v_and_b32_e32 v0, 0xffff0000, v29
	v_cndmask_b32_e64 v149, 0, v0, s[30:31]
	s_waitcnt vmcnt(41)
	v_lshlrev_b32_e32 v0, 16, v32
	v_cndmask_b32_e64 v152, 0, v0, s[36:37]
	v_and_b32_e32 v0, 0xffff0000, v32
	v_cndmask_b32_e64 v153, 0, v0, s[36:37]
	s_waitcnt vmcnt(40)
	v_lshlrev_b32_e32 v0, 16, v38
	v_cndmask_b32_e64 v154, 0, v0, s[50:51]
	v_and_b32_e32 v0, 0xffff0000, v38
	v_cndmask_b32_e64 v155, 0, v0, s[50:51]
	s_waitcnt vmcnt(39)
	v_lshlrev_b32_e32 v0, 16, v43
	v_cndmask_b32_e64 v156, 0, v0, s[58:59]
	v_and_b32_e32 v0, 0xffff0000, v43
	v_cndmask_b32_e64 v142, 0, v142, s[0:1]
	v_cndmask_b32_e64 v157, 0, v0, s[58:59]
	s_waitcnt vmcnt(38)
	v_lshlrev_b32_e32 v0, 16, v119
	v_pk_fma_f32 v[142:143], v[54:55], v[142:143], v[112:113]
	v_cndmask_b32_e32 v158, 0, v0, vcc
	v_and_b32_e32 v0, 0xffff0000, v119
	v_pk_fma_f32 v[142:143], v[56:57], v[144:145], v[142:143]
	v_pk_fma_f32 v[144:145], v[54:55], v[144:145], v[112:113]
	v_cndmask_b32_e32 v159, 0, v0, vcc
	s_waitcnt vmcnt(37)
	v_lshlrev_b32_e32 v0, 16, v134
	v_pk_fma_f32 v[142:143], v[58:59], v[146:147], v[142:143]
	v_pk_fma_f32 v[144:145], v[56:57], v[146:147], v[144:145]
	v_pk_fma_f32 v[146:147], v[54:55], v[146:147], v[112:113]
	v_cndmask_b32_e64 v160, 0, v0, s[70:71]
	v_and_b32_e32 v0, 0xffff0000, v134
	v_pk_fma_f32 v[142:143], v[50:51], v[148:149], v[142:143]
	v_pk_fma_f32 v[144:145], v[58:59], v[148:149], v[144:145]
	v_pk_fma_f32 v[146:147], v[56:57], v[148:149], v[146:147]
	v_pk_fma_f32 v[148:149], v[54:55], v[148:149], v[112:113]
	v_cndmask_b32_e64 v161, 0, v0, s[70:71]
	s_waitcnt vmcnt(36)
	v_lshlrev_b32_e32 v0, 16, v137
	v_pk_fma_f32 v[142:143], v[52:53], v[152:153], v[142:143]
	v_pk_fma_f32 v[144:145], v[50:51], v[152:153], v[144:145]
	v_pk_fma_f32 v[146:147], v[58:59], v[152:153], v[146:147]
	v_pk_fma_f32 v[148:149], v[56:57], v[152:153], v[148:149]
	v_pk_fma_f32 v[152:153], v[54:55], v[152:153], v[112:113]
	v_cndmask_b32_e64 v162, 0, v0, s[76:77]
	v_and_b32_e32 v0, 0xffff0000, v137
	v_pk_fma_f32 v[142:143], v[60:61], v[154:155], v[142:143]
	v_pk_fma_f32 v[144:145], v[52:53], v[154:155], v[144:145]
	v_pk_fma_f32 v[146:147], v[50:51], v[154:155], v[146:147]
	v_pk_fma_f32 v[148:149], v[58:59], v[154:155], v[148:149]
	v_pk_fma_f32 v[152:153], v[56:57], v[154:155], v[152:153]
	v_pk_fma_f32 v[154:155], v[54:55], v[154:155], v[112:113]
	v_cndmask_b32_e64 v163, 0, v0, s[76:77]
	s_waitcnt vmcnt(35)
	v_lshlrev_b32_e32 v0, 16, v138
	v_pk_fma_f32 v[142:143], v[62:63], v[156:157], v[142:143]
	v_pk_fma_f32 v[144:145], v[60:61], v[156:157], v[144:145]
	v_pk_fma_f32 v[146:147], v[52:53], v[156:157], v[146:147]
	v_pk_fma_f32 v[148:149], v[50:51], v[156:157], v[148:149]
	v_pk_fma_f32 v[152:153], v[58:59], v[156:157], v[152:153]
	v_pk_fma_f32 v[154:155], v[56:57], v[156:157], v[154:155]
	v_pk_fma_f32 v[156:157], v[54:55], v[156:157], v[112:113]
	v_cndmask_b32_e64 v164, 0, v0, s[78:79]
	v_and_b32_e32 v0, 0xffff0000, v138
	v_pk_fma_f32 v[142:143], v[64:65], v[158:159], v[142:143]
	v_pk_fma_f32 v[144:145], v[62:63], v[158:159], v[144:145]
	v_pk_fma_f32 v[146:147], v[60:61], v[158:159], v[146:147]
	v_pk_fma_f32 v[148:149], v[52:53], v[158:159], v[148:149]
	v_pk_fma_f32 v[152:153], v[50:51], v[158:159], v[152:153]
	v_pk_fma_f32 v[154:155], v[58:59], v[158:159], v[154:155]
	v_pk_fma_f32 v[156:157], v[56:57], v[158:159], v[156:157]
	v_pk_fma_f32 v[158:159], v[54:55], v[158:159], v[112:113]
	v_cndmask_b32_e64 v165, 0, v0, s[78:79]
	s_waitcnt vmcnt(34)
	v_lshlrev_b32_e32 v0, 16, v135
	v_pk_fma_f32 v[142:143], v[66:67], v[160:161], v[142:143]
	v_pk_fma_f32 v[144:145], v[64:65], v[160:161], v[144:145]
	v_pk_fma_f32 v[146:147], v[62:63], v[160:161], v[146:147]
	v_pk_fma_f32 v[148:149], v[60:61], v[160:161], v[148:149]
	v_pk_fma_f32 v[152:153], v[52:53], v[160:161], v[152:153]
	v_pk_fma_f32 v[154:155], v[50:51], v[160:161], v[154:155]
	v_pk_fma_f32 v[156:157], v[58:59], v[160:161], v[156:157]
	v_pk_fma_f32 v[158:159], v[56:57], v[160:161], v[158:159]
	v_pk_fma_f32 v[160:161], v[54:55], v[160:161], v[112:113]
	v_cndmask_b32_e32 v134, 0, v0, vcc
	v_and_b32_e32 v0, 0xffff0000, v135
	v_pk_fma_f32 v[142:143], v[68:69], v[162:163], v[142:143]
	v_pk_fma_f32 v[144:145], v[66:67], v[162:163], v[144:145]
	v_pk_fma_f32 v[146:147], v[64:65], v[162:163], v[146:147]
	v_pk_fma_f32 v[148:149], v[62:63], v[162:163], v[148:149]
	v_pk_fma_f32 v[152:153], v[60:61], v[162:163], v[152:153]
	v_pk_fma_f32 v[154:155], v[52:53], v[162:163], v[154:155]
	v_pk_fma_f32 v[156:157], v[50:51], v[162:163], v[156:157]
	v_pk_fma_f32 v[158:159], v[58:59], v[162:163], v[158:159]
	v_pk_fma_f32 v[160:161], v[56:57], v[162:163], v[160:161]
	v_pk_fma_f32 v[162:163], v[54:55], v[162:163], v[112:113]
	v_cndmask_b32_e32 v135, 0, v0, vcc
	s_waitcnt vmcnt(33)
	v_lshlrev_b32_e32 v0, 16, v136
	v_pk_fma_f32 v[142:143], v[70:71], v[164:165], v[142:143]
	v_pk_fma_f32 v[144:145], v[68:69], v[164:165], v[144:145]
	v_pk_fma_f32 v[146:147], v[66:67], v[164:165], v[146:147]
	v_pk_fma_f32 v[148:149], v[64:65], v[164:165], v[148:149]
	v_pk_fma_f32 v[152:153], v[62:63], v[164:165], v[152:153]
	v_pk_fma_f32 v[154:155], v[60:61], v[164:165], v[154:155]
	v_pk_fma_f32 v[156:157], v[52:53], v[164:165], v[156:157]
	v_pk_fma_f32 v[158:159], v[50:51], v[164:165], v[158:159]
	v_pk_fma_f32 v[160:161], v[58:59], v[164:165], v[160:161]
	v_pk_fma_f32 v[162:163], v[56:57], v[164:165], v[162:163]
	v_pk_fma_f32 v[164:165], v[54:55], v[164:165], v[112:113]
	v_cndmask_b32_e64 v166, 0, v0, s[74:75]
	v_and_b32_e32 v0, 0xffff0000, v136
	v_pk_fma_f32 v[142:143], v[72:73], v[134:135], v[142:143]
	v_pk_fma_f32 v[144:145], v[70:71], v[134:135], v[144:145]
	v_pk_fma_f32 v[146:147], v[68:69], v[134:135], v[146:147]
	v_pk_fma_f32 v[148:149], v[66:67], v[134:135], v[148:149]
	v_pk_fma_f32 v[152:153], v[64:65], v[134:135], v[152:153]
	v_pk_fma_f32 v[154:155], v[62:63], v[134:135], v[154:155]
	v_pk_fma_f32 v[156:157], v[60:61], v[134:135], v[156:157]
	v_pk_fma_f32 v[158:159], v[52:53], v[134:135], v[158:159]
	v_pk_fma_f32 v[160:161], v[50:51], v[134:135], v[160:161]
	v_pk_fma_f32 v[162:163], v[58:59], v[134:135], v[162:163]
	v_pk_fma_f32 v[164:165], v[56:57], v[134:135], v[164:165]
	v_pk_fma_f32 v[134:135], v[54:55], v[134:135], v[112:113]
	v_cndmask_b32_e64 v167, 0, v0, s[74:75]
	s_waitcnt vmcnt(32)
	v_lshlrev_b32_e32 v0, 16, v121
	v_pk_fma_f32 v[136:137], v[74:75], v[166:167], v[142:143]
	v_pk_fma_f32 v[142:143], v[72:73], v[166:167], v[144:145]
	v_pk_fma_f32 v[144:145], v[70:71], v[166:167], v[146:147]
	v_pk_fma_f32 v[146:147], v[68:69], v[166:167], v[148:149]
	v_pk_fma_f32 v[148:149], v[66:67], v[166:167], v[152:153]
	v_pk_fma_f32 v[152:153], v[64:65], v[166:167], v[154:155]
	v_pk_fma_f32 v[154:155], v[62:63], v[166:167], v[156:157]
	v_pk_fma_f32 v[156:157], v[60:61], v[166:167], v[158:159]
	v_pk_fma_f32 v[158:159], v[52:53], v[166:167], v[160:161]
	v_pk_fma_f32 v[160:161], v[50:51], v[166:167], v[162:163]
	v_pk_fma_f32 v[162:163], v[58:59], v[166:167], v[164:165]
	v_pk_fma_f32 v[134:135], v[56:57], v[166:167], v[134:135]
	v_pk_fma_f32 v[164:165], v[54:55], v[166:167], v[112:113]
	v_cndmask_b32_e32 v166, 0, v0, vcc
	v_and_b32_e32 v0, 0xffff0000, v121
	s_cmp_ge_i32 s2, s89
	v_cndmask_b32_e32 v167, 0, v0, vcc
	s_waitcnt vmcnt(31)
	v_lshlrev_b32_e32 v0, 16, v49
	s_cselect_b64 s[0:1], -1, 0
	s_cmp_lt_i32 s2, s88
	v_cndmask_b32_e32 v168, 0, v0, vcc
	v_and_b32_e32 v0, 0xffff0000, v49
	s_cselect_b64 s[6:7], -1, 0
	v_cndmask_b32_e32 v169, 0, v0, vcc
	s_waitcnt vmcnt(30)
	v_lshlrev_b32_e32 v0, 16, v47
	s_and_b64 vcc, s[0:1], s[6:7]
	v_cndmask_b32_e32 v170, 0, v0, vcc
	v_and_b32_e32 v0, 0xffff0000, v47
	v_pk_fma_f32 v[136:137], v[76:77], v[166:167], v[136:137]
	v_pk_fma_f32 v[142:143], v[74:75], v[166:167], v[142:143]
	v_pk_fma_f32 v[144:145], v[72:73], v[166:167], v[144:145]
	v_pk_fma_f32 v[146:147], v[70:71], v[166:167], v[146:147]
	v_pk_fma_f32 v[148:149], v[68:69], v[166:167], v[148:149]
	v_pk_fma_f32 v[152:153], v[66:67], v[166:167], v[152:153]
	v_pk_fma_f32 v[154:155], v[64:65], v[166:167], v[154:155]
	v_pk_fma_f32 v[156:157], v[62:63], v[166:167], v[156:157]
	v_pk_fma_f32 v[158:159], v[60:61], v[166:167], v[158:159]
	v_pk_fma_f32 v[160:161], v[52:53], v[166:167], v[160:161]
	v_pk_fma_f32 v[162:163], v[50:51], v[166:167], v[162:163]
	v_pk_fma_f32 v[134:135], v[58:59], v[166:167], v[134:135]
	v_pk_fma_f32 v[164:165], v[56:57], v[166:167], v[164:165]
	v_pk_fma_f32 v[166:167], v[54:55], v[166:167], v[112:113]
	v_cndmask_b32_e32 v171, 0, v0, vcc
	s_waitcnt vmcnt(29)
	v_lshlrev_b32_e32 v0, 16, v48
	v_pk_fma_f32 v[136:137], v[78:79], v[168:169], v[136:137]
	v_pk_fma_f32 v[142:143], v[76:77], v[168:169], v[142:143]
	v_pk_fma_f32 v[144:145], v[74:75], v[168:169], v[144:145]
	v_pk_fma_f32 v[146:147], v[72:73], v[168:169], v[146:147]
	v_pk_fma_f32 v[148:149], v[70:71], v[168:169], v[148:149]
	v_pk_fma_f32 v[152:153], v[68:69], v[168:169], v[152:153]
	v_pk_fma_f32 v[154:155], v[66:67], v[168:169], v[154:155]
	v_pk_fma_f32 v[156:157], v[64:65], v[168:169], v[156:157]
	v_pk_fma_f32 v[158:159], v[62:63], v[168:169], v[158:159]
	v_pk_fma_f32 v[160:161], v[60:61], v[168:169], v[160:161]
	v_pk_fma_f32 v[162:163], v[52:53], v[168:169], v[162:163]
	v_pk_fma_f32 v[134:135], v[50:51], v[168:169], v[134:135]
	v_pk_fma_f32 v[164:165], v[58:59], v[168:169], v[164:165]
	v_pk_fma_f32 v[166:167], v[56:57], v[168:169], v[166:167]
	v_pk_fma_f32 v[168:169], v[54:55], v[168:169], v[112:113]
	v_cndmask_b32_e64 v172, 0, v0, s[64:65]
	v_and_b32_e32 v0, 0xffff0000, v48
	v_pk_fma_f32 v[136:137], v[80:81], v[170:171], v[136:137]
	v_pk_fma_f32 v[142:143], v[78:79], v[170:171], v[142:143]
	v_pk_fma_f32 v[144:145], v[76:77], v[170:171], v[144:145]
	v_pk_fma_f32 v[146:147], v[74:75], v[170:171], v[146:147]
	v_pk_fma_f32 v[148:149], v[72:73], v[170:171], v[148:149]
	v_pk_fma_f32 v[152:153], v[70:71], v[170:171], v[152:153]
	v_pk_fma_f32 v[154:155], v[68:69], v[170:171], v[154:155]
	v_pk_fma_f32 v[156:157], v[66:67], v[170:171], v[156:157]
	v_pk_fma_f32 v[158:159], v[64:65], v[170:171], v[158:159]
	v_pk_fma_f32 v[160:161], v[62:63], v[170:171], v[160:161]
	v_pk_fma_f32 v[162:163], v[60:61], v[170:171], v[162:163]
	v_pk_fma_f32 v[134:135], v[52:53], v[170:171], v[134:135]
	v_pk_fma_f32 v[164:165], v[50:51], v[170:171], v[164:165]
	v_pk_fma_f32 v[166:167], v[58:59], v[170:171], v[166:167]
	v_pk_fma_f32 v[168:169], v[56:57], v[170:171], v[168:169]
	v_pk_fma_f32 v[170:171], v[54:55], v[170:171], v[112:113]
	v_cndmask_b32_e64 v173, 0, v0, s[64:65]
	s_waitcnt vmcnt(28)
	v_lshlrev_b32_e32 v0, 16, v46
	v_pk_fma_f32 v[48:49], v[82:83], v[172:173], v[136:137]
	v_pk_fma_f32 v[136:137], v[80:81], v[172:173], v[142:143]
	v_pk_fma_f32 v[142:143], v[78:79], v[172:173], v[144:145]
	v_pk_fma_f32 v[144:145], v[76:77], v[172:173], v[146:147]
	v_pk_fma_f32 v[146:147], v[74:75], v[172:173], v[148:149]
	v_pk_fma_f32 v[148:149], v[72:73], v[172:173], v[152:153]
	v_pk_fma_f32 v[152:153], v[70:71], v[172:173], v[154:155]
	v_pk_fma_f32 v[154:155], v[68:69], v[172:173], v[156:157]
	v_pk_fma_f32 v[156:157], v[66:67], v[172:173], v[158:159]
	v_pk_fma_f32 v[158:159], v[64:65], v[172:173], v[160:161]
	v_pk_fma_f32 v[160:161], v[62:63], v[172:173], v[162:163]
	v_pk_fma_f32 v[162:163], v[52:53], v[172:173], v[164:165]
	v_pk_fma_f32 v[164:165], v[50:51], v[172:173], v[166:167]
	v_pk_fma_f32 v[166:167], v[58:59], v[172:173], v[168:169]
	v_pk_fma_f32 v[168:169], v[56:57], v[172:173], v[170:171]
	v_cndmask_b32_e64 v170, 0, v0, s[62:63]
	v_and_b32_e32 v0, 0xffff0000, v46
	v_cndmask_b32_e64 v171, 0, v0, s[62:63]
	s_waitcnt vmcnt(27)
	v_lshlrev_b32_e32 v0, 16, v44
	v_pk_fma_f32 v[134:135], v[60:61], v[172:173], v[134:135]
	v_pk_fma_f32 v[46:47], v[84:85], v[170:171], v[48:49]
	v_pk_fma_f32 v[48:49], v[82:83], v[170:171], v[136:137]
	v_pk_fma_f32 v[136:137], v[80:81], v[170:171], v[142:143]
	v_pk_fma_f32 v[142:143], v[78:79], v[170:171], v[144:145]
	v_pk_fma_f32 v[144:145], v[76:77], v[170:171], v[146:147]
	v_pk_fma_f32 v[146:147], v[74:75], v[170:171], v[148:149]
	v_pk_fma_f32 v[148:149], v[72:73], v[170:171], v[152:153]
	v_pk_fma_f32 v[152:153], v[70:71], v[170:171], v[154:155]
	v_pk_fma_f32 v[154:155], v[68:69], v[170:171], v[156:157]
	v_pk_fma_f32 v[156:157], v[66:67], v[170:171], v[158:159]
	v_pk_fma_f32 v[158:159], v[64:65], v[170:171], v[160:161]
	v_pk_fma_f32 v[160:161], v[60:61], v[170:171], v[162:163]
	v_pk_fma_f32 v[162:163], v[52:53], v[170:171], v[164:165]
	v_pk_fma_f32 v[164:165], v[50:51], v[170:171], v[166:167]
	v_pk_fma_f32 v[166:167], v[58:59], v[170:171], v[168:169]
	v_cndmask_b32_e64 v168, 0, v0, s[60:61]
	v_and_b32_e32 v0, 0xffff0000, v44
	v_pk_fma_f32 v[134:135], v[62:63], v[170:171], v[134:135]
	v_cndmask_b32_e64 v169, 0, v0, s[60:61]
	s_waitcnt vmcnt(26)
	v_lshlrev_b32_e32 v0, 16, v42
	v_pk_fma_f32 v[46:47], v[86:87], v[168:169], v[46:47]
	v_pk_fma_f32 v[48:49], v[84:85], v[168:169], v[48:49]
	v_pk_fma_f32 v[136:137], v[82:83], v[168:169], v[136:137]
	v_pk_fma_f32 v[142:143], v[80:81], v[168:169], v[142:143]
	v_pk_fma_f32 v[144:145], v[78:79], v[168:169], v[144:145]
	v_pk_fma_f32 v[146:147], v[76:77], v[168:169], v[146:147]
	v_pk_fma_f32 v[148:149], v[74:75], v[168:169], v[148:149]
	v_pk_fma_f32 v[152:153], v[72:73], v[168:169], v[152:153]
	v_pk_fma_f32 v[154:155], v[70:71], v[168:169], v[154:155]
	v_pk_fma_f32 v[156:157], v[68:69], v[168:169], v[156:157]
	v_pk_fma_f32 v[158:159], v[66:67], v[168:169], v[158:159]
	v_pk_fma_f32 v[134:135], v[64:65], v[168:169], v[134:135]
	v_pk_fma_f32 v[160:161], v[62:63], v[168:169], v[160:161]
	v_pk_fma_f32 v[162:163], v[60:61], v[168:169], v[162:163]
	v_pk_fma_f32 v[164:165], v[52:53], v[168:169], v[164:165]
	v_pk_fma_f32 v[166:167], v[50:51], v[168:169], v[166:167]
	v_cndmask_b32_e64 v168, 0, v0, s[56:57]
	v_and_b32_e32 v0, 0xffff0000, v42
	v_cndmask_b32_e64 v169, 0, v0, s[56:57]
	s_waitcnt vmcnt(25)
	v_lshlrev_b32_e32 v0, 16, v39
	v_cndmask_b32_e64 v38, 0, v0, s[52:53]
	v_and_b32_e32 v0, 0xffff0000, v39
	v_pk_fma_f32 v[42:43], v[88:89], v[168:169], v[46:47]
	v_pk_fma_f32 v[46:47], v[86:87], v[168:169], v[48:49]
	v_pk_fma_f32 v[48:49], v[84:85], v[168:169], v[136:137]
	v_pk_fma_f32 v[136:137], v[82:83], v[168:169], v[142:143]
	v_pk_fma_f32 v[142:143], v[80:81], v[168:169], v[144:145]
	v_pk_fma_f32 v[144:145], v[78:79], v[168:169], v[146:147]
	v_pk_fma_f32 v[146:147], v[76:77], v[168:169], v[148:149]
	v_pk_fma_f32 v[148:149], v[74:75], v[168:169], v[152:153]
	v_pk_fma_f32 v[152:153], v[72:73], v[168:169], v[154:155]
	v_pk_fma_f32 v[154:155], v[70:71], v[168:169], v[156:157]
	v_pk_fma_f32 v[156:157], v[68:69], v[168:169], v[158:159]
	v_pk_fma_f32 v[134:135], v[66:67], v[168:169], v[134:135]
	v_pk_fma_f32 v[158:159], v[64:65], v[168:169], v[160:161]
	v_pk_fma_f32 v[160:161], v[62:63], v[168:169], v[162:163]
	v_pk_fma_f32 v[162:163], v[60:61], v[168:169], v[164:165]
	v_pk_fma_f32 v[164:165], v[52:53], v[168:169], v[166:167]
	v_cndmask_b32_e64 v39, 0, v0, s[52:53]
	s_waitcnt vmcnt(24)
	v_lshlrev_b32_e32 v0, 16, v36
	v_pk_fma_f32 v[42:43], v[90:91], v[38:39], v[42:43]
	v_pk_fma_f32 v[46:47], v[88:89], v[38:39], v[46:47]
	v_pk_fma_f32 v[48:49], v[86:87], v[38:39], v[48:49]
	v_pk_fma_f32 v[136:137], v[84:85], v[38:39], v[136:137]
	v_pk_fma_f32 v[142:143], v[82:83], v[38:39], v[142:143]
	v_pk_fma_f32 v[144:145], v[80:81], v[38:39], v[144:145]
	v_pk_fma_f32 v[146:147], v[78:79], v[38:39], v[146:147]
	v_pk_fma_f32 v[148:149], v[76:77], v[38:39], v[148:149]
	v_pk_fma_f32 v[152:153], v[74:75], v[38:39], v[152:153]
	v_pk_fma_f32 v[154:155], v[72:73], v[38:39], v[154:155]
	v_pk_fma_f32 v[156:157], v[70:71], v[38:39], v[156:157]
	v_pk_fma_f32 v[134:135], v[68:69], v[38:39], v[134:135]
	v_pk_fma_f32 v[158:159], v[66:67], v[38:39], v[158:159]
	v_pk_fma_f32 v[160:161], v[64:65], v[38:39], v[160:161]
	v_pk_fma_f32 v[162:163], v[62:63], v[38:39], v[162:163]
	v_pk_fma_f32 v[38:39], v[60:61], v[38:39], v[164:165]
	v_cndmask_b32_e64 v164, 0, v0, s[44:45]
	v_and_b32_e32 v0, 0xffff0000, v36
	v_cndmask_b32_e64 v165, 0, v0, s[44:45]
	s_waitcnt vmcnt(23)
	v_lshlrev_b32_e32 v0, 16, v33
	v_cndmask_b32_e64 v32, 0, v0, s[38:39]
	v_and_b32_e32 v0, 0xffff0000, v33
	v_pk_fma_f32 v[42:43], v[92:93], v[164:165], v[42:43]
	v_pk_fma_f32 v[46:47], v[90:91], v[164:165], v[46:47]
	v_pk_fma_f32 v[48:49], v[88:89], v[164:165], v[48:49]
	v_pk_fma_f32 v[136:137], v[86:87], v[164:165], v[136:137]
	v_pk_fma_f32 v[142:143], v[84:85], v[164:165], v[142:143]
	v_pk_fma_f32 v[144:145], v[82:83], v[164:165], v[144:145]
	v_pk_fma_f32 v[146:147], v[80:81], v[164:165], v[146:147]
	v_pk_fma_f32 v[148:149], v[78:79], v[164:165], v[148:149]
	v_pk_fma_f32 v[152:153], v[76:77], v[164:165], v[152:153]
	v_pk_fma_f32 v[154:155], v[74:75], v[164:165], v[154:155]
	v_pk_fma_f32 v[156:157], v[72:73], v[164:165], v[156:157]
	v_pk_fma_f32 v[134:135], v[70:71], v[164:165], v[134:135]
	v_pk_fma_f32 v[158:159], v[68:69], v[164:165], v[158:159]
	v_pk_fma_f32 v[160:161], v[66:67], v[164:165], v[160:161]
	v_pk_fma_f32 v[162:163], v[64:65], v[164:165], v[162:163]
	v_pk_fma_f32 v[38:39], v[62:63], v[164:165], v[38:39]
	v_cndmask_b32_e64 v33, 0, v0, s[38:39]
	s_waitcnt vmcnt(22)
	v_lshlrev_b32_e32 v0, 16, v40
	v_pk_fma_f32 v[42:43], v[94:95], v[32:33], v[42:43]
	v_pk_fma_f32 v[46:47], v[92:93], v[32:33], v[46:47]
	v_pk_fma_f32 v[48:49], v[90:91], v[32:33], v[48:49]
	v_pk_fma_f32 v[136:137], v[88:89], v[32:33], v[136:137]
	v_pk_fma_f32 v[142:143], v[86:87], v[32:33], v[142:143]
	v_pk_fma_f32 v[144:145], v[84:85], v[32:33], v[144:145]
	v_pk_fma_f32 v[146:147], v[82:83], v[32:33], v[146:147]
	v_pk_fma_f32 v[148:149], v[80:81], v[32:33], v[148:149]
	v_pk_fma_f32 v[152:153], v[78:79], v[32:33], v[152:153]
	v_pk_fma_f32 v[154:155], v[76:77], v[32:33], v[154:155]
	v_pk_fma_f32 v[156:157], v[74:75], v[32:33], v[156:157]
	v_pk_fma_f32 v[134:135], v[72:73], v[32:33], v[134:135]
	v_pk_fma_f32 v[158:159], v[70:71], v[32:33], v[158:159]
	v_pk_fma_f32 v[160:161], v[68:69], v[32:33], v[160:161]
	v_pk_fma_f32 v[162:163], v[66:67], v[32:33], v[162:163]
	v_pk_fma_f32 v[32:33], v[64:65], v[32:33], v[38:39]
	v_cndmask_b32_e64 v38, 0, v0, s[24:25]
	v_and_b32_e32 v0, 0xffff0000, v40
	v_cndmask_b32_e64 v39, 0, v0, s[24:25]
	s_waitcnt vmcnt(21)
	v_lshlrev_b32_e32 v0, 16, v41
	v_pk_fma_f32 v[42:43], v[96:97], v[38:39], v[42:43]
	v_pk_fma_f32 v[46:47], v[94:95], v[38:39], v[46:47]
	v_pk_fma_f32 v[48:49], v[92:93], v[38:39], v[48:49]
	v_pk_fma_f32 v[136:137], v[90:91], v[38:39], v[136:137]
	v_pk_fma_f32 v[142:143], v[88:89], v[38:39], v[142:143]
	v_pk_fma_f32 v[144:145], v[86:87], v[38:39], v[144:145]
	v_pk_fma_f32 v[146:147], v[84:85], v[38:39], v[146:147]
	v_pk_fma_f32 v[148:149], v[82:83], v[38:39], v[148:149]
	v_pk_fma_f32 v[152:153], v[80:81], v[38:39], v[152:153]
	v_pk_fma_f32 v[154:155], v[78:79], v[38:39], v[154:155]
	v_pk_fma_f32 v[156:157], v[76:77], v[38:39], v[156:157]
	v_pk_fma_f32 v[134:135], v[74:75], v[38:39], v[134:135]
	v_pk_fma_f32 v[158:159], v[72:73], v[38:39], v[158:159]
	v_pk_fma_f32 v[160:161], v[70:71], v[38:39], v[160:161]
	v_pk_fma_f32 v[162:163], v[68:69], v[38:39], v[162:163]
	v_pk_fma_f32 v[32:33], v[66:67], v[38:39], v[32:33]
	v_cndmask_b32_e64 v38, 0, v0, s[54:55]
	v_and_b32_e32 v0, 0xffff0000, v41
	v_cndmask_b32_e64 v39, 0, v0, s[54:55]
	s_waitcnt vmcnt(20)
	v_lshlrev_b32_e32 v0, 16, v37
	v_cndmask_b32_e64 v36, 0, v0, s[48:49]
	v_and_b32_e32 v0, 0xffff0000, v37
	v_pk_fma_f32 v[40:41], v[98:99], v[38:39], v[42:43]
	v_pk_fma_f32 v[42:43], v[96:97], v[38:39], v[46:47]
	v_pk_fma_f32 v[46:47], v[94:95], v[38:39], v[48:49]
	v_pk_fma_f32 v[48:49], v[92:93], v[38:39], v[136:137]
	v_pk_fma_f32 v[136:137], v[90:91], v[38:39], v[142:143]
	v_pk_fma_f32 v[142:143], v[88:89], v[38:39], v[144:145]
	v_pk_fma_f32 v[144:145], v[86:87], v[38:39], v[146:147]
	v_pk_fma_f32 v[146:147], v[84:85], v[38:39], v[148:149]
	v_pk_fma_f32 v[148:149], v[82:83], v[38:39], v[152:153]
	v_pk_fma_f32 v[152:153], v[80:81], v[38:39], v[154:155]
	v_pk_fma_f32 v[154:155], v[78:79], v[38:39], v[156:157]
	v_pk_fma_f32 v[134:135], v[76:77], v[38:39], v[134:135]
	v_pk_fma_f32 v[156:157], v[74:75], v[38:39], v[158:159]
	v_pk_fma_f32 v[158:159], v[72:73], v[38:39], v[160:161]
	v_pk_fma_f32 v[160:161], v[70:71], v[38:39], v[162:163]
	v_pk_fma_f32 v[32:33], v[68:69], v[38:39], v[32:33]
	v_cndmask_b32_e64 v37, 0, v0, s[48:49]
	s_waitcnt vmcnt(19)
	v_lshlrev_b32_e32 v0, 16, v35
	v_pk_fma_f32 v[38:39], v[100:101], v[36:37], v[40:41]
	v_pk_fma_f32 v[40:41], v[98:99], v[36:37], v[42:43]
	v_pk_fma_f32 v[42:43], v[96:97], v[36:37], v[46:47]
	v_pk_fma_f32 v[46:47], v[94:95], v[36:37], v[48:49]
	v_pk_fma_f32 v[48:49], v[92:93], v[36:37], v[136:137]
	v_pk_fma_f32 v[136:137], v[90:91], v[36:37], v[142:143]
	v_pk_fma_f32 v[142:143], v[88:89], v[36:37], v[144:145]
	v_pk_fma_f32 v[144:145], v[86:87], v[36:37], v[146:147]
	v_pk_fma_f32 v[146:147], v[84:85], v[36:37], v[148:149]
	v_pk_fma_f32 v[148:149], v[82:83], v[36:37], v[152:153]
	v_pk_fma_f32 v[152:153], v[80:81], v[36:37], v[154:155]
	v_pk_fma_f32 v[134:135], v[78:79], v[36:37], v[134:135]
	v_pk_fma_f32 v[154:155], v[76:77], v[36:37], v[156:157]
	v_pk_fma_f32 v[156:157], v[74:75], v[36:37], v[158:159]
	v_pk_fma_f32 v[158:159], v[72:73], v[36:37], v[160:161]
	v_pk_fma_f32 v[32:33], v[70:71], v[36:37], v[32:33]
	v_cndmask_b32_e64 v36, 0, v0, s[42:43]
	v_and_b32_e32 v0, 0xffff0000, v35
	v_cndmask_b32_e64 v37, 0, v0, s[42:43]
	s_waitcnt vmcnt(18)
	v_lshlrev_b32_e32 v0, 16, v30
	v_pk_fma_f32 v[38:39], v[102:103], v[36:37], v[38:39]
	v_pk_fma_f32 v[40:41], v[100:101], v[36:37], v[40:41]
	v_pk_fma_f32 v[42:43], v[98:99], v[36:37], v[42:43]
	v_pk_fma_f32 v[46:47], v[96:97], v[36:37], v[46:47]
	v_pk_fma_f32 v[48:49], v[94:95], v[36:37], v[48:49]
	v_pk_fma_f32 v[136:137], v[92:93], v[36:37], v[136:137]
	v_pk_fma_f32 v[142:143], v[90:91], v[36:37], v[142:143]
	v_pk_fma_f32 v[144:145], v[88:89], v[36:37], v[144:145]
	v_pk_fma_f32 v[146:147], v[86:87], v[36:37], v[146:147]
	v_pk_fma_f32 v[148:149], v[84:85], v[36:37], v[148:149]
	v_pk_fma_f32 v[152:153], v[82:83], v[36:37], v[152:153]
	v_pk_fma_f32 v[134:135], v[80:81], v[36:37], v[134:135]
	v_pk_fma_f32 v[154:155], v[78:79], v[36:37], v[154:155]
	v_pk_fma_f32 v[156:157], v[76:77], v[36:37], v[156:157]
	v_pk_fma_f32 v[158:159], v[74:75], v[36:37], v[158:159]
	v_pk_fma_f32 v[32:33], v[72:73], v[36:37], v[32:33]
	v_cndmask_b32_e64 v36, 0, v0, s[34:35]
	v_and_b32_e32 v0, 0xffff0000, v30
	v_cndmask_b32_e64 v37, 0, v0, s[34:35]
	s_waitcnt vmcnt(17)
	v_lshlrev_b32_e32 v0, 16, v22
	v_pk_fma_f32 v[38:39], v[104:105], v[36:37], v[38:39]
	v_pk_fma_f32 v[40:41], v[102:103], v[36:37], v[40:41]
	v_pk_fma_f32 v[42:43], v[100:101], v[36:37], v[42:43]
	v_pk_fma_f32 v[46:47], v[98:99], v[36:37], v[46:47]
	v_pk_fma_f32 v[48:49], v[96:97], v[36:37], v[48:49]
	v_pk_fma_f32 v[136:137], v[94:95], v[36:37], v[136:137]
	v_pk_fma_f32 v[142:143], v[92:93], v[36:37], v[142:143]
	v_pk_fma_f32 v[144:145], v[90:91], v[36:37], v[144:145]
	v_pk_fma_f32 v[146:147], v[88:89], v[36:37], v[146:147]
	v_pk_fma_f32 v[148:149], v[86:87], v[36:37], v[148:149]
	v_pk_fma_f32 v[152:153], v[84:85], v[36:37], v[152:153]
	v_pk_fma_f32 v[134:135], v[82:83], v[36:37], v[134:135]
	v_pk_fma_f32 v[154:155], v[80:81], v[36:37], v[154:155]
	v_pk_fma_f32 v[156:157], v[78:79], v[36:37], v[156:157]
	v_pk_fma_f32 v[158:159], v[76:77], v[36:37], v[158:159]
	v_pk_fma_f32 v[32:33], v[74:75], v[36:37], v[32:33]
	v_cndmask_b32_e64 v36, 0, v0, s[14:15]
	v_and_b32_e32 v0, 0xffff0000, v22
	v_cndmask_b32_e64 v37, 0, v0, s[14:15]
	s_waitcnt vmcnt(16)
	v_lshlrev_b32_e32 v0, 16, v20
	v_pk_fma_f32 v[38:39], v[106:107], v[36:37], v[38:39]
	v_pk_fma_f32 v[40:41], v[104:105], v[36:37], v[40:41]
	v_pk_fma_f32 v[42:43], v[102:103], v[36:37], v[42:43]
	v_pk_fma_f32 v[46:47], v[100:101], v[36:37], v[46:47]
	v_pk_fma_f32 v[48:49], v[98:99], v[36:37], v[48:49]
	v_pk_fma_f32 v[136:137], v[96:97], v[36:37], v[136:137]
	v_pk_fma_f32 v[142:143], v[94:95], v[36:37], v[142:143]
	v_pk_fma_f32 v[144:145], v[92:93], v[36:37], v[144:145]
	v_pk_fma_f32 v[146:147], v[90:91], v[36:37], v[146:147]
	v_pk_fma_f32 v[148:149], v[88:89], v[36:37], v[148:149]
	v_pk_fma_f32 v[152:153], v[86:87], v[36:37], v[152:153]
	v_pk_fma_f32 v[134:135], v[84:85], v[36:37], v[134:135]
	v_pk_fma_f32 v[154:155], v[82:83], v[36:37], v[154:155]
	v_pk_fma_f32 v[156:157], v[80:81], v[36:37], v[156:157]
	v_pk_fma_f32 v[158:159], v[78:79], v[36:37], v[158:159]
	v_pk_fma_f32 v[32:33], v[76:77], v[36:37], v[32:33]
	v_cndmask_b32_e64 v36, 0, v0, s[10:11]
	v_and_b32_e32 v0, 0xffff0000, v20
	v_cndmask_b32_e64 v37, 0, v0, s[10:11]
	s_waitcnt vmcnt(15)
	v_lshlrev_b32_e32 v0, 16, v19
	v_cndmask_b32_e64 v18, 0, v0, s[8:9]
	v_and_b32_e32 v0, 0xffff0000, v19
	v_pk_fma_f32 v[20:21], v[108:109], v[36:37], v[38:39]
	v_pk_fma_f32 v[38:39], v[106:107], v[36:37], v[40:41]
	v_pk_fma_f32 v[40:41], v[104:105], v[36:37], v[42:43]
	v_pk_fma_f32 v[42:43], v[102:103], v[36:37], v[46:47]
	v_pk_fma_f32 v[46:47], v[100:101], v[36:37], v[48:49]
	v_pk_fma_f32 v[48:49], v[98:99], v[36:37], v[136:137]
	v_pk_fma_f32 v[136:137], v[96:97], v[36:37], v[142:143]
	v_pk_fma_f32 v[142:143], v[94:95], v[36:37], v[144:145]
	v_pk_fma_f32 v[144:145], v[92:93], v[36:37], v[146:147]
	v_pk_fma_f32 v[146:147], v[90:91], v[36:37], v[148:149]
	v_pk_fma_f32 v[148:149], v[88:89], v[36:37], v[152:153]
	v_pk_fma_f32 v[134:135], v[86:87], v[36:37], v[134:135]
	v_pk_fma_f32 v[152:153], v[84:85], v[36:37], v[154:155]
	v_pk_fma_f32 v[154:155], v[82:83], v[36:37], v[156:157]
	v_pk_fma_f32 v[156:157], v[80:81], v[36:37], v[158:159]
	v_pk_fma_f32 v[32:33], v[78:79], v[36:37], v[32:33]
	v_cndmask_b32_e64 v19, 0, v0, s[8:9]
	s_waitcnt vmcnt(14)
	v_lshlrev_b32_e32 v0, 16, v27
	v_pk_fma_f32 v[20:21], v[110:111], v[18:19], v[20:21]
	v_pk_fma_f32 v[36:37], v[108:109], v[18:19], v[38:39]
	v_pk_fma_f32 v[38:39], v[106:107], v[18:19], v[40:41]
	v_pk_fma_f32 v[40:41], v[104:105], v[18:19], v[42:43]
	v_pk_fma_f32 v[42:43], v[102:103], v[18:19], v[46:47]
	v_pk_fma_f32 v[46:47], v[100:101], v[18:19], v[48:49]
	v_pk_fma_f32 v[48:49], v[98:99], v[18:19], v[136:137]
	v_pk_fma_f32 v[136:137], v[96:97], v[18:19], v[142:143]
	v_pk_fma_f32 v[142:143], v[94:95], v[18:19], v[144:145]
	v_pk_fma_f32 v[144:145], v[92:93], v[18:19], v[146:147]
	v_pk_fma_f32 v[146:147], v[90:91], v[18:19], v[148:149]
	v_pk_fma_f32 v[134:135], v[88:89], v[18:19], v[134:135]
	v_pk_fma_f32 v[148:149], v[86:87], v[18:19], v[152:153]
	v_pk_fma_f32 v[152:153], v[84:85], v[18:19], v[154:155]
	v_pk_fma_f32 v[154:155], v[82:83], v[18:19], v[156:157]
	v_pk_fma_f32 v[18:19], v[80:81], v[18:19], v[32:33]
	v_cndmask_b32_e64 v32, 0, v0, s[4:5]
	v_and_b32_e32 v0, 0xffff0000, v27
	v_cndmask_b32_e64 v33, 0, v0, s[4:5]
	s_waitcnt vmcnt(13)
	v_lshlrev_b32_e32 v0, 16, v31
	v_cndmask_b32_e64 v30, 0, v0, s[26:27]
	v_and_b32_e32 v0, 0xffff0000, v31
	v_pk_fma_f32 v[38:39], v[108:109], v[32:33], v[38:39]
	v_pk_fma_f32 v[40:41], v[106:107], v[32:33], v[40:41]
	v_pk_fma_f32 v[42:43], v[104:105], v[32:33], v[42:43]
	v_pk_fma_f32 v[46:47], v[102:103], v[32:33], v[46:47]
	v_pk_fma_f32 v[48:49], v[100:101], v[32:33], v[48:49]
	v_pk_fma_f32 v[136:137], v[98:99], v[32:33], v[136:137]
	v_pk_fma_f32 v[142:143], v[96:97], v[32:33], v[142:143]
	v_pk_fma_f32 v[144:145], v[94:95], v[32:33], v[144:145]
	v_pk_fma_f32 v[146:147], v[92:93], v[32:33], v[146:147]
	v_pk_fma_f32 v[134:135], v[90:91], v[32:33], v[134:135]
	v_pk_fma_f32 v[148:149], v[88:89], v[32:33], v[148:149]
	v_pk_fma_f32 v[152:153], v[86:87], v[32:33], v[152:153]
	v_pk_fma_f32 v[154:155], v[84:85], v[32:33], v[154:155]
	v_pk_fma_f32 v[18:19], v[82:83], v[32:33], v[18:19]
	v_cndmask_b32_e64 v31, 0, v0, s[26:27]
	s_waitcnt vmcnt(12)
	v_lshlrev_b32_e32 v0, 16, v25
	v_pk_fma_f32 v[36:37], v[110:111], v[32:33], v[36:37]
	v_pk_fma_f32 v[32:33], v[110:111], v[30:31], v[38:39]
	v_pk_fma_f32 v[38:39], v[108:109], v[30:31], v[40:41]
	v_pk_fma_f32 v[40:41], v[106:107], v[30:31], v[42:43]
	v_pk_fma_f32 v[42:43], v[104:105], v[30:31], v[46:47]
	v_pk_fma_f32 v[46:47], v[102:103], v[30:31], v[48:49]
	v_pk_fma_f32 v[48:49], v[100:101], v[30:31], v[136:137]
	v_pk_fma_f32 v[136:137], v[98:99], v[30:31], v[142:143]
	v_pk_fma_f32 v[142:143], v[96:97], v[30:31], v[144:145]
	v_pk_fma_f32 v[144:145], v[94:95], v[30:31], v[146:147]
	v_pk_fma_f32 v[134:135], v[92:93], v[30:31], v[134:135]
	v_pk_fma_f32 v[146:147], v[90:91], v[30:31], v[148:149]
	v_pk_fma_f32 v[148:149], v[88:89], v[30:31], v[152:153]
	v_pk_fma_f32 v[152:153], v[86:87], v[30:31], v[154:155]
	v_pk_fma_f32 v[18:19], v[84:85], v[30:31], v[18:19]
	v_cndmask_b32_e64 v30, 0, v0, s[20:21]
	v_and_b32_e32 v0, 0xffff0000, v25
	v_cndmask_b32_e64 v31, 0, v0, s[20:21]
	s_waitcnt vmcnt(11)
	v_lshlrev_b32_e32 v0, 16, v23
	v_cndmask_b32_e64 v22, 0, v0, s[16:17]
	v_and_b32_e32 v0, 0xffff0000, v23
	v_pk_fma_f32 v[40:41], v[108:109], v[30:31], v[40:41]
	v_pk_fma_f32 v[42:43], v[106:107], v[30:31], v[42:43]
	v_pk_fma_f32 v[46:47], v[104:105], v[30:31], v[46:47]
	v_pk_fma_f32 v[48:49], v[102:103], v[30:31], v[48:49]
	v_pk_fma_f32 v[136:137], v[100:101], v[30:31], v[136:137]
	v_pk_fma_f32 v[142:143], v[98:99], v[30:31], v[142:143]
	v_pk_fma_f32 v[144:145], v[96:97], v[30:31], v[144:145]
	v_pk_fma_f32 v[134:135], v[94:95], v[30:31], v[134:135]
	v_pk_fma_f32 v[146:147], v[92:93], v[30:31], v[146:147]
	v_pk_fma_f32 v[148:149], v[90:91], v[30:31], v[148:149]
	v_pk_fma_f32 v[152:153], v[88:89], v[30:31], v[152:153]
	v_pk_fma_f32 v[18:19], v[86:87], v[30:31], v[18:19]
	v_cndmask_b32_e64 v23, 0, v0, s[16:17]
	s_waitcnt vmcnt(10)
	v_lshlrev_b32_e32 v0, 16, v24
	v_pk_fma_f32 v[38:39], v[110:111], v[30:31], v[38:39]
	v_pk_fma_f32 v[30:31], v[110:111], v[22:23], v[40:41]
	v_pk_fma_f32 v[40:41], v[108:109], v[22:23], v[42:43]
	v_pk_fma_f32 v[42:43], v[106:107], v[22:23], v[46:47]
	v_pk_fma_f32 v[46:47], v[104:105], v[22:23], v[48:49]
	v_pk_fma_f32 v[48:49], v[102:103], v[22:23], v[136:137]
	v_pk_fma_f32 v[136:137], v[100:101], v[22:23], v[142:143]
	v_pk_fma_f32 v[142:143], v[98:99], v[22:23], v[144:145]
	v_pk_fma_f32 v[134:135], v[96:97], v[22:23], v[134:135]
	v_pk_fma_f32 v[144:145], v[94:95], v[22:23], v[146:147]
	v_pk_fma_f32 v[146:147], v[92:93], v[22:23], v[148:149]
	v_pk_fma_f32 v[148:149], v[90:91], v[22:23], v[152:153]
	v_pk_fma_f32 v[18:19], v[88:89], v[22:23], v[18:19]
	v_cndmask_b32_e64 v22, 0, v0, s[18:19]
	v_and_b32_e32 v0, 0xffff0000, v24
	v_cndmask_b32_e64 v23, 0, v0, s[18:19]
	s_waitcnt vmcnt(9)
	v_lshlrev_b32_e32 v0, 16, v26
	v_pk_fma_f32 v[24:25], v[110:111], v[22:23], v[40:41]
	v_pk_fma_f32 v[40:41], v[108:109], v[22:23], v[42:43]
	v_pk_fma_f32 v[42:43], v[106:107], v[22:23], v[46:47]
	v_pk_fma_f32 v[46:47], v[104:105], v[22:23], v[48:49]
	v_pk_fma_f32 v[48:49], v[102:103], v[22:23], v[136:137]
	v_pk_fma_f32 v[136:137], v[100:101], v[22:23], v[142:143]
	v_pk_fma_f32 v[134:135], v[98:99], v[22:23], v[134:135]
	v_pk_fma_f32 v[142:143], v[96:97], v[22:23], v[144:145]
	v_pk_fma_f32 v[144:145], v[94:95], v[22:23], v[146:147]
	v_pk_fma_f32 v[146:147], v[92:93], v[22:23], v[148:149]
	v_pk_fma_f32 v[18:19], v[90:91], v[22:23], v[18:19]
	v_cndmask_b32_e64 v22, 0, v0, s[22:23]
	v_and_b32_e32 v0, 0xffff0000, v26
	v_cndmask_b32_e64 v23, 0, v0, s[22:23]
	s_waitcnt vmcnt(8)
	v_lshlrev_b32_e32 v0, 16, v28
	v_pk_fma_f32 v[26:27], v[110:111], v[22:23], v[40:41]
	v_pk_fma_f32 v[40:41], v[108:109], v[22:23], v[42:43]
	v_pk_fma_f32 v[42:43], v[106:107], v[22:23], v[46:47]
	v_pk_fma_f32 v[46:47], v[104:105], v[22:23], v[48:49]
	v_pk_fma_f32 v[48:49], v[102:103], v[22:23], v[136:137]
	v_pk_fma_f32 v[134:135], v[100:101], v[22:23], v[134:135]
	v_pk_fma_f32 v[136:137], v[98:99], v[22:23], v[142:143]
	v_pk_fma_f32 v[142:143], v[96:97], v[22:23], v[144:145]
	v_pk_fma_f32 v[144:145], v[94:95], v[22:23], v[146:147]
	v_pk_fma_f32 v[18:19], v[92:93], v[22:23], v[18:19]
	v_cndmask_b32_e64 v22, 0, v0, s[28:29]
	v_and_b32_e32 v0, 0xffff0000, v28
	v_cndmask_b32_e64 v23, 0, v0, s[28:29]
	s_waitcnt vmcnt(7)
	v_lshlrev_b32_e32 v0, 16, v34
	v_pk_fma_f32 v[28:29], v[110:111], v[22:23], v[40:41]
	v_pk_fma_f32 v[40:41], v[108:109], v[22:23], v[42:43]
	v_pk_fma_f32 v[42:43], v[106:107], v[22:23], v[46:47]
	v_pk_fma_f32 v[46:47], v[104:105], v[22:23], v[48:49]
	v_pk_fma_f32 v[48:49], v[102:103], v[22:23], v[134:135]
	v_pk_fma_f32 v[134:135], v[100:101], v[22:23], v[136:137]
	v_pk_fma_f32 v[136:137], v[98:99], v[22:23], v[142:143]
	v_pk_fma_f32 v[142:143], v[96:97], v[22:23], v[144:145]
	v_pk_fma_f32 v[18:19], v[94:95], v[22:23], v[18:19]
	v_cndmask_b32_e64 v22, 0, v0, s[40:41]
	v_and_b32_e32 v0, 0xffff0000, v34
	v_cndmask_b32_e64 v23, 0, v0, s[40:41]
	s_waitcnt vmcnt(6)
	v_lshlrev_b32_e32 v0, 16, v45
	v_pk_fma_f32 v[34:35], v[110:111], v[22:23], v[40:41]
	v_pk_fma_f32 v[40:41], v[108:109], v[22:23], v[42:43]
	v_pk_fma_f32 v[42:43], v[106:107], v[22:23], v[46:47]
	v_pk_fma_f32 v[46:47], v[104:105], v[22:23], v[48:49]
	v_pk_fma_f32 v[48:49], v[102:103], v[22:23], v[134:135]
	v_pk_fma_f32 v[134:135], v[100:101], v[22:23], v[136:137]
	v_pk_fma_f32 v[136:137], v[98:99], v[22:23], v[142:143]
	v_pk_fma_f32 v[18:19], v[96:97], v[22:23], v[18:19]
	v_cndmask_b32_e64 v22, 0, v0, s[46:47]
	v_and_b32_e32 v0, 0xffff0000, v45
	v_cndmask_b32_e64 v23, 0, v0, s[46:47]
	s_waitcnt vmcnt(5)
	v_lshlrev_b32_e32 v0, 16, v118
	v_pk_fma_f32 v[40:41], v[110:111], v[22:23], v[40:41]
	v_pk_fma_f32 v[42:43], v[108:109], v[22:23], v[42:43]
	v_pk_fma_f32 v[44:45], v[106:107], v[22:23], v[46:47]
	v_pk_fma_f32 v[46:47], v[104:105], v[22:23], v[48:49]
	v_pk_fma_f32 v[48:49], v[102:103], v[22:23], v[134:135]
	v_pk_fma_f32 v[134:135], v[100:101], v[22:23], v[136:137]
	v_pk_fma_f32 v[18:19], v[98:99], v[22:23], v[18:19]
	v_cndmask_b32_e64 v22, 0, v0, s[66:67]
	v_and_b32_e32 v0, 0xffff0000, v118
	v_cndmask_b32_e64 v23, 0, v0, s[66:67]
	s_waitcnt vmcnt(4)
	v_lshlrev_b32_e32 v0, 16, v120
	v_pk_fma_f32 v[42:43], v[110:111], v[22:23], v[42:43]
	v_pk_fma_f32 v[44:45], v[108:109], v[22:23], v[44:45]
	v_pk_fma_f32 v[46:47], v[106:107], v[22:23], v[46:47]
	v_pk_fma_f32 v[48:49], v[104:105], v[22:23], v[48:49]
	v_pk_fma_f32 v[118:119], v[102:103], v[22:23], v[134:135]
	v_pk_fma_f32 v[18:19], v[100:101], v[22:23], v[18:19]
	v_cndmask_b32_e64 v22, 0, v0, s[68:69]
	v_and_b32_e32 v0, 0xffff0000, v120
	v_cndmask_b32_e64 v23, 0, v0, s[68:69]
	s_waitcnt vmcnt(3)
	v_lshlrev_b32_e32 v0, 16, v133
	v_pk_fma_f32 v[44:45], v[110:111], v[22:23], v[44:45]
	v_pk_fma_f32 v[46:47], v[108:109], v[22:23], v[46:47]
	v_pk_fma_f32 v[48:49], v[106:107], v[22:23], v[48:49]
	v_pk_fma_f32 v[118:119], v[104:105], v[22:23], v[118:119]
	v_pk_fma_f32 v[18:19], v[102:103], v[22:23], v[18:19]
	v_cndmask_b32_e64 v22, 0, v0, s[72:73]
	v_and_b32_e32 v0, 0xffff0000, v133
	v_cndmask_b32_e64 v23, 0, v0, s[72:73]
	s_waitcnt vmcnt(2)
	v_lshlrev_b32_e32 v0, 16, v139
	v_pk_fma_f32 v[46:47], v[110:111], v[22:23], v[46:47]
	v_pk_fma_f32 v[48:49], v[108:109], v[22:23], v[48:49]
	v_pk_fma_f32 v[118:119], v[106:107], v[22:23], v[118:119]
	v_pk_fma_f32 v[18:19], v[104:105], v[22:23], v[18:19]
	v_cndmask_b32_e64 v22, 0, v0, s[80:81]
	v_and_b32_e32 v0, 0xffff0000, v139
	v_cndmask_b32_e64 v23, 0, v0, s[80:81]
	s_waitcnt vmcnt(1)
	v_lshlrev_b32_e32 v0, 16, v140
	v_pk_fma_f32 v[48:49], v[110:111], v[22:23], v[48:49]
	v_pk_fma_f32 v[118:119], v[108:109], v[22:23], v[118:119]
	v_pk_fma_f32 v[18:19], v[106:107], v[22:23], v[18:19]
	v_cndmask_b32_e64 v22, 0, v0, s[82:83]
	v_and_b32_e32 v0, 0xffff0000, v140
	v_cndmask_b32_e64 v23, 0, v0, s[82:83]
	s_waitcnt vmcnt(0)
	v_lshlrev_b32_e32 v0, 16, v141
	v_pk_fma_f32 v[118:119], v[110:111], v[22:23], v[118:119]
	v_pk_fma_f32 v[18:19], v[108:109], v[22:23], v[18:19]
	v_cndmask_b32_e64 v22, 0, v0, s[84:85]
	v_and_b32_e32 v0, 0xffff0000, v141
	v_cndmask_b32_e64 v23, 0, v0, s[84:85]
	v_pk_fma_f32 v[18:19], v[110:111], v[22:23], v[18:19]
	ds_write2st64_b64 v122, v[20:21], v[36:37] offset1:8
	ds_write2st64_b64 v122, v[32:33], v[38:39] offset0:16 offset1:24
	ds_write2st64_b64 v122, v[30:31], v[24:25] offset0:32 offset1:40
	ds_write2st64_b64 v122, v[26:27], v[28:29] offset0:48 offset1:56
	ds_write2st64_b64 v122, v[34:35], v[40:41] offset0:64 offset1:72
	ds_write2st64_b64 v122, v[42:43], v[44:45] offset0:80 offset1:88
	ds_write2st64_b64 v122, v[46:47], v[48:49] offset0:96 offset1:104
	ds_write2st64_b64 v122, v[118:119], v[18:19] offset0:112 offset1:120
	s_waitcnt lgkmcnt(0)
	s_barrier
	ds_read_b128 v[46:49], v131
	ds_read_b128 v[42:45], v131 offset:1024
	ds_read_b128 v[38:41], v131 offset:2048
	ds_read_b128 v[34:37], v131 offset:3072
	ds_read_b128 v[30:33], v132
	ds_read_b128 v[26:29], v132 offset:1024
	s_waitcnt lgkmcnt(5)
	v_mov_b32_e32 v18, v47
	v_mov_b32_e32 v19, v48
	v_mov_b32_e32 v20, v46
	v_mov_b32_e32 v21, v49
	v_pk_add_f32 v[18:19], v[18:19], v[20:21]
	s_waitcnt lgkmcnt(4)
	v_mov_b32_e32 v20, v43
	v_mov_b32_e32 v21, v44
	v_mov_b32_e32 v22, v42
	v_mov_b32_e32 v23, v45
	v_pk_add_f32 v[20:21], v[20:21], v[22:23]
	v_add_f32_e32 v0, v18, v19
	v_pk_add_f32 v[20:21], v[20:21], v[20:21] op_sel:[0,1] op_sel_hi:[1,0]
	v_add_f32_e32 v18, 0, v0
	s_waitcnt lgkmcnt(3)
	v_add_f32_e32 v22, v38, v39
	v_add_f32_e32 v24, v40, v41
	s_waitcnt lgkmcnt(2)
	v_mov_b32_e32 v19, v34
	v_mov_b32_e32 v21, v35
	v_mov_b32_e32 v23, v36
	v_mov_b32_e32 v25, v37
	v_pk_add_f32 v[18:19], v[18:19], v[20:21]
	v_pk_add_f32 v[20:21], v[22:23], v[24:25]
	s_waitcnt lgkmcnt(0)
	v_mov_b32_e32 v136, v27
	v_pk_add_f32 v[18:19], v[18:19], v[20:21]
	v_mov_b32_e32 v137, v28
	v_add_f32_e32 v0, v18, v19
	ds_bpermute_b32 v18, v124, v0
	v_mov_b32_e32 v138, v26
	v_mov_b32_e32 v139, v29
	v_pk_add_f32 v[136:137], v[136:137], v[138:139]
	s_mov_b32 s0, 0x3a800000
	s_waitcnt lgkmcnt(0)
	v_add_f32_e32 v0, v0, v18
	ds_bpermute_b32 v18, v125, v0
	v_pk_add_f32 v[136:137], v[136:137], v[136:137] op_sel:[0,1] op_sel_hi:[1,0]
	s_mov_b32 s50, 0x800000
	s_add_i32 s94, s94, s96
	s_mov_b32 s70, s96
	s_waitcnt lgkmcnt(0)
	v_add_f32_e32 v0, v0, v18
	ds_bpermute_b32 v18, v126, v0
	s_mov_b32 s84, s97
	s_waitcnt lgkmcnt(0)
	v_add_f32_e32 v0, v0, v18
	ds_bpermute_b32 v18, v127, v0
	s_waitcnt lgkmcnt(0)
	v_add_f32_e32 v0, v0, v18
	ds_bpermute_b32 v18, v128, v0
	s_waitcnt lgkmcnt(0)
	v_add_f32_e32 v0, v0, v18
	ds_bpermute_b32 v18, v129, v0
	s_waitcnt lgkmcnt(0)
	v_add_f32_e32 v133, v0, v18
	v_fmamk_f32 v121, v133, 0xba800000, v47
	v_fmamk_f32 v120, v133, 0xba800000, v46
	v_fmamk_f32 v49, v133, 0xba800000, v49
	v_fmac_f32_e32 v48, 0xba800000, v133
	v_pk_mul_f32 v[18:19], v[48:49], v[48:49]
	v_pk_mul_f32 v[20:21], v[120:121], v[120:121]
	v_fmamk_f32 v47, v133, 0xba800000, v43
	v_pk_mov_b32 v[22:23], v[20:21], v[18:19] op_sel:[1,0]
	v_mov_b32_e32 v21, v19
	v_pk_add_f32 v[18:19], v[22:23], v[20:21]
	v_mov_b32_e32 v20, v30
	v_pk_add_f32 v[134:135], v[18:19], v[18:19] op_sel_hi:[0,1]
	v_mov_b32_e32 v18, v31
	v_mov_b32_e32 v19, v32
	v_mov_b32_e32 v21, v33
	v_pk_add_f32 v[18:19], v[18:19], v[20:21]
	ds_read_b128 v[22:25], v132 offset:2048
	v_add_f32_e32 v0, v18, v19
	ds_read_b128 v[18:21], v132 offset:3072
	v_add_f32_e32 v118, 0, v0
	v_fmamk_f32 v46, v133, 0xba800000, v42
	s_waitcnt lgkmcnt(1)
	v_add_f32_e32 v138, v22, v23
	v_add_f32_e32 v140, v24, v25
	s_waitcnt lgkmcnt(0)
	v_mov_b32_e32 v119, v18
	v_mov_b32_e32 v137, v19
	v_mov_b32_e32 v139, v20
	v_mov_b32_e32 v141, v21
	v_pk_add_f32 v[118:119], v[118:119], v[136:137]
	v_pk_add_f32 v[136:137], v[138:139], v[140:141]
	v_fmamk_f32 v45, v133, 0xba800000, v45
	v_pk_add_f32 v[118:119], v[118:119], v[136:137]
	v_fmac_f32_e32 v44, 0xba800000, v133
	v_add_f32_e32 v0, v118, v119
	ds_bpermute_b32 v134, v124, v0
	v_pk_mul_f32 v[42:43], v[44:45], v[44:45]
	v_pk_mul_f32 v[118:119], v[46:47], v[46:47]
	v_fmac_f32_e32 v40, 0xba800000, v133
	v_pk_mov_b32 v[136:137], v[118:119], v[42:43] op_sel:[1,0]
	s_waitcnt lgkmcnt(0)
	v_add_f32_e32 v0, v0, v134
	ds_bpermute_b32 v134, v125, v0
	v_mov_b32_e32 v119, v43
	v_pk_add_f32 v[42:43], v[136:137], v[118:119]
	v_fmamk_f32 v118, v133, 0xba800000, v38
	v_pk_add_f32 v[42:43], v[42:43], v[42:43] op_sel_hi:[0,1]
	s_waitcnt lgkmcnt(0)
	v_add_f32_e32 v42, v0, v134
	ds_bpermute_b32 v134, v126, v42
	v_fmamk_f32 v119, v133, 0xba800000, v39
	v_mul_f32_e32 v0, v118, v118
	v_pk_fma_f32 v[38:39], v[118:119], v[118:119], v[0:1] op_sel_hi:[1,1,0]
	v_fmamk_f32 v41, v133, 0xba800000, v41
	s_waitcnt lgkmcnt(0)
	v_add_f32_e32 v38, v42, v134
	ds_bpermute_b32 v42, v127, v38
	v_mul_f32_e32 v0, v40, v40
	v_pk_fma_f32 v[136:137], v[40:41], v[40:41], v[0:1] op_sel_hi:[1,1,0]
	v_fmamk_f32 v37, v133, 0xba800000, v37
	v_fmamk_f32 v36, v133, 0xba800000, v36
	s_waitcnt lgkmcnt(0)
	v_add_f32_e32 v0, v38, v42
	ds_bpermute_b32 v42, v128, v0
	v_fmamk_f32 v35, v133, 0xba800000, v35
	v_fmac_f32_e32 v34, 0xba800000, v133
	v_mul_f32_e32 v38, v34, v34
	v_mul_f32_e32 v136, v35, v35
	s_waitcnt lgkmcnt(0)
	v_add_f32_e32 v0, v0, v42
	ds_bpermute_b32 v133, v129, v0
	v_mul_f32_e32 v134, v36, v36
	v_mul_f32_e32 v42, v37, v37
	v_pk_add_f32 v[38:39], v[38:39], v[136:137]
	v_pk_add_f32 v[42:43], v[134:135], v[42:43]
	s_waitcnt lgkmcnt(0)
	v_add_f32_e32 v133, v0, v133
	v_fmamk_f32 v31, v133, 0xba800000, v31
	v_fmamk_f32 v30, v133, 0xba800000, v30
	v_fmamk_f32 v33, v133, 0xba800000, v33
	v_fmac_f32_e32 v32, 0xba800000, v133
	v_pk_add_f32 v[38:39], v[38:39], v[42:43]
	v_pk_mul_f32 v[42:43], v[32:33], v[32:33]
	v_pk_mul_f32 v[134:135], v[30:31], v[30:31]
	v_fmamk_f32 v27, v133, 0xba800000, v27
	v_pk_mov_b32 v[136:137], v[134:135], v[42:43] op_sel:[1,0]
	v_mov_b32_e32 v135, v43
	v_fmamk_f32 v26, v133, 0xba800000, v26
	v_fmamk_f32 v29, v133, 0xba800000, v29
	v_fmac_f32_e32 v28, 0xba800000, v133
	v_pk_add_f32 v[42:43], v[136:137], v[134:135]
	v_pk_mul_f32 v[134:135], v[28:29], v[28:29]
	v_pk_mul_f32 v[136:137], v[26:27], v[26:27]
	v_fmamk_f32 v22, v133, 0xba800000, v22
	v_pk_mov_b32 v[138:139], v[136:137], v[134:135] op_sel:[1,0]
	v_mov_b32_e32 v137, v135
	v_fmamk_f32 v23, v133, 0xba800000, v23
	v_fmac_f32_e32 v24, 0xba800000, v133
	v_mul_f32_e32 v0, v22, v22
	v_pk_add_f32 v[134:135], v[138:139], v[136:137]
	v_fmamk_f32 v25, v133, 0xba800000, v25
	v_pk_fma_f32 v[136:137], v[22:23], v[22:23], v[0:1] op_sel_hi:[1,1,0]
	v_mul_f32_e32 v0, v24, v24
	v_pk_add_f32 v[42:43], v[42:43], v[42:43] op_sel_hi:[0,1]
	v_pk_add_f32 v[134:135], v[134:135], v[134:135] op_sel_hi:[0,1]
	v_pk_fma_f32 v[138:139], v[24:25], v[24:25], v[0:1] op_sel_hi:[1,1,0]
	v_fmamk_f32 v21, v133, 0xba800000, v21
	v_fmamk_f32 v20, v133, 0xba800000, v20
	v_fmamk_f32 v19, v133, 0xba800000, v19
	v_fmac_f32_e32 v18, 0xba800000, v133
	v_mul_f32_e32 v136, v18, v18
	v_mul_f32_e32 v138, v19, v19
	v_mul_f32_e32 v42, v20, v20
	v_mul_f32_e32 v134, v21, v21
	v_pk_add_f32 v[136:137], v[136:137], v[138:139]
	v_pk_add_f32 v[42:43], v[42:43], v[134:135]
	v_mov_b32_e32 v135, v38
	v_pk_add_f32 v[42:43], v[136:137], v[42:43]
	s_nop 0
	v_mov_b32_e32 v134, v42
	v_mov_b32_e32 v38, v43
	v_pk_add_f32 v[38:39], v[134:135], v[38:39]
	ds_bpermute_b32 v43, v124, v39
	ds_bpermute_b32 v42, v124, v38
	v_add_u32_e32 v134, s2, v123
	v_ashrrev_i32_e32 v135, 31, v134
	v_lshlrev_b64 v[134:135], 11, v[134:135]
	s_waitcnt lgkmcnt(0)
	v_pk_add_f32 v[38:39], v[38:39], v[42:43]
	ds_bpermute_b32 v43, v125, v39
	ds_bpermute_b32 v42, v125, v38
	s_waitcnt lgkmcnt(0)
	v_pk_add_f32 v[38:39], v[38:39], v[42:43]
	ds_bpermute_b32 v43, v126, v39
	ds_bpermute_b32 v42, v126, v38
	s_waitcnt lgkmcnt(0)
	v_pk_add_f32 v[38:39], v[38:39], v[42:43]
	ds_bpermute_b32 v43, v127, v39
	ds_bpermute_b32 v42, v127, v38
	s_waitcnt lgkmcnt(0)
	v_pk_add_f32 v[38:39], v[38:39], v[42:43]
	ds_bpermute_b32 v43, v128, v39
	ds_bpermute_b32 v42, v128, v38
	s_waitcnt lgkmcnt(0)
	v_pk_add_f32 v[38:39], v[38:39], v[42:43]
	ds_bpermute_b32 v43, v129, v39
	ds_bpermute_b32 v42, v129, v38
	s_waitcnt lgkmcnt(0)
	v_pk_add_f32 v[38:39], v[38:39], v[42:43]
	s_nop 0
	v_pk_fma_f32 v[38:39], v[38:39], s[0:1], v[150:151] op_sel_hi:[1,0,0]
	s_nop 0
	v_mul_f32_e32 v0, 0x4b800000, v39
	v_cmp_gt_f32_e32 vcc, s50, v39
	s_nop 1
	v_cndmask_b32_e32 v0, v39, v0, vcc
	v_rsq_f32_e32 v0, v0
	s_nop 0
	v_mul_f32_e32 v39, 0x45800000, v0
	v_cndmask_b32_e32 v0, v0, v39, vcc
	v_pk_mul_f32 v[42:43], v[120:121], v[0:1] op_sel_hi:[1,0]
	v_pk_mul_f32 v[48:49], v[48:49], v[0:1] op_sel_hi:[1,0]
	v_pk_mul_f32 v[120:121], v[2:3], v[42:43]
	v_pk_mul_f32 v[48:49], v[4:5], v[48:49]
	v_mul_f32_e32 v39, 0xbfb8aa3b, v120
	v_exp_f32_e32 v42, v39
	v_mul_f32_e32 v39, 0xbfb8aa3b, v121
	v_exp_f32_e32 v43, v39
	v_pk_mul_f32 v[46:47], v[46:47], v[0:1] op_sel_hi:[1,0]
	v_pk_mul_f32 v[44:45], v[44:45], v[0:1] op_sel_hi:[1,0]
	v_pk_mul_f32 v[46:47], v[6:7], v[46:47]
	v_pk_add_f32 v[136:137], v[42:43], 1.0 op_sel_hi:[1,0]
	v_lshl_add_u64 v[42:43], v[116:117], 0, v[134:135]
	v_pk_mul_f32 v[44:45], v[8:9], v[44:45]
	v_pk_mul_f32 v[40:41], v[40:41], v[0:1] op_sel_hi:[1,0]
	v_pk_mul_f32 v[34:35], v[34:35], v[0:1] op_sel_hi:[1,0]
	v_mul_f32_e32 v134, 0xbfb8aa3b, v48
	v_mul_f32_e32 v135, 0xbfb8aa3b, v49
	v_exp_f32_e32 v134, v134
	v_exp_f32_e32 v135, v135
	v_rcp_f32_e32 v39, v137
	s_nop 0
	v_mul_f32_e32 v39, v121, v39
	v_pk_add_f32 v[134:135], v[134:135], 1.0 op_sel_hi:[1,0]
	v_rcp_f32_e32 v121, v136
	s_nop 0
	v_mul_f32_e32 v133, v120, v121
	v_pk_mul_f32 v[40:41], v[12:13], v[40:41]
	v_rcp_f32_e32 v120, v135
	s_nop 0
	v_mul_f32_e32 v49, v49, v120
	v_pk_mul_f32 v[34:35], v[14:15], v[34:35]
	v_mul_f32_e32 v120, 0xbfb8aa3b, v46
	v_mul_f32_e32 v121, 0xbfb8aa3b, v47
	v_exp_f32_e32 v120, v120
	v_exp_f32_e32 v121, v121
	v_rcp_f32_e32 v135, v134
	s_nop 0
	v_mul_f32_e32 v134, v48, v135
	v_cvt_pk_bf16_f32 v48, v133, v39
	v_cvt_pk_bf16_f32 v49, v134, v49
	v_pk_add_f32 v[120:121], v[120:121], 1.0 op_sel_hi:[1,0]
	global_store_dwordx2 v[42:43], v[48:49], off
	v_pk_mul_f32 v[36:37], v[36:37], v[0:1] op_sel_hi:[1,0]
	v_mul_f32_e32 v48, 0xbfb8aa3b, v44
	v_mul_f32_e32 v49, 0xbfb8aa3b, v45
	v_exp_f32_e32 v48, v48
	v_exp_f32_e32 v49, v49
	v_rcp_f32_e32 v39, v121
	s_nop 0
	v_mul_f32_e32 v39, v47, v39
	v_pk_add_f32 v[48:49], v[48:49], 1.0 op_sel_hi:[1,0]
	v_rcp_f32_e32 v47, v120
	s_nop 0
	v_mul_f32_e32 v120, v46, v47
	v_pk_mul_f32 v[36:37], v[16:17], v[36:37]
	v_rcp_f32_e32 v46, v49
	s_nop 0
	v_mul_f32_e32 v45, v45, v46
	v_pk_mul_f32 v[46:47], v[118:119], v[0:1] op_sel_hi:[1,0]
	v_rcp_f32_e32 v49, v48
	s_nop 0
	v_mul_f32_e32 v48, v44, v49
	v_pk_mul_f32 v[46:47], v[10:11], v[46:47]
	v_cvt_pk_bf16_f32 v45, v48, v45
	v_mul_f32_e32 v118, 0xbfb8aa3b, v46
	v_mul_f32_e32 v119, 0xbfb8aa3b, v47
	v_exp_f32_e32 v118, v118
	v_exp_f32_e32 v119, v119
	v_cvt_pk_bf16_f32 v44, v120, v39
	global_store_dwordx2 v[42:43], v[44:45], off offset:512
	v_pk_add_f32 v[48:49], v[118:119], 1.0 op_sel_hi:[1,0]
	s_nop 0
	s_nop 0
	v_mul_f32_e32 v45, 0xbfb8aa3b, v41
	v_mul_f32_e32 v44, 0xbfb8aa3b, v40
	v_exp_f32_e32 v44, v44
	v_exp_f32_e32 v45, v45
	v_rcp_f32_e32 v39, v49
	s_nop 0
	v_mul_f32_e32 v39, v47, v39
	v_pk_add_f32 v[44:45], v[44:45], 1.0 op_sel_hi:[1,0]
	v_rcp_f32_e32 v47, v48
	s_nop 0
	v_mul_f32_e32 v48, v46, v47
	v_rcp_f32_e32 v46, v45
	s_nop 0
	v_mul_f32_e32 v41, v41, v46
	v_mul_f32_e32 v46, 0xbfb8aa3b, v34
	v_mul_f32_e32 v47, 0xbfb8aa3b, v35
	v_exp_f32_e32 v46, v46
	v_exp_f32_e32 v47, v47
	v_rcp_f32_e32 v45, v44
	s_nop 0
	v_mul_f32_e32 v44, v40, v45
	v_cvt_pk_bf16_f32 v41, v44, v41
	v_cvt_pk_bf16_f32 v40, v48, v39
	v_pk_add_f32 v[44:45], v[46:47], 1.0 op_sel_hi:[1,0]
	global_store_dwordx2 v[42:43], v[40:41], off offset:1024
	s_nop 0
	v_mul_f32_e32 v40, 0xbfb8aa3b, v36
	v_mul_f32_e32 v41, 0xbfb8aa3b, v37
	v_rcp_f32_e32 v0, v45
	s_nop 0
	v_mul_f32_e32 v0, v35, v0
	v_exp_f32_e32 v40, v40
	v_exp_f32_e32 v41, v41
	s_nop 0
	v_pk_add_f32 v[40:41], v[40:41], 1.0 op_sel_hi:[1,0]
	v_rcp_f32_e32 v35, v44
	s_nop 0
	v_mul_f32_e32 v34, v34, v35
	v_cvt_pk_bf16_f32 v34, v34, v0
	v_rcp_f32_e32 v35, v41
	s_nop 0
	v_mul_f32_e32 v35, v37, v35
	v_rcp_f32_e32 v37, v40
	s_nop 0
	v_mul_f32_e32 v36, v36, v37
	v_mul_f32_e32 v37, 0x4b800000, v38
	v_cmp_gt_f32_e32 vcc, s50, v38
	v_cvt_pk_bf16_f32 v35, v36, v35
	global_store_dwordx2 v[42:43], v[34:35], off offset:1536
	v_cndmask_b32_e32 v37, v38, v37, vcc
	v_rsq_f32_e32 v37, v37
	v_add_u32_e32 v36, s2, v130
	s_add_i32 s2, s2, s97
	v_mul_f32_e32 v0, 0x45800000, v37
	v_cndmask_b32_e32 v0, v37, v0, vcc
	v_pk_mul_f32 v[30:31], v[30:31], v[0:1] op_sel_hi:[1,0]
	v_ashrrev_i32_e32 v37, 31, v36
	v_pk_mul_f32 v[34:35], v[2:3], v[30:31]
	v_lshlrev_b64 v[36:37], 11, v[36:37]
	v_mul_f32_e32 v30, 0xbfb8aa3b, v34
	v_mul_f32_e32 v31, 0xbfb8aa3b, v35
	v_exp_f32_e32 v30, v30
	v_exp_f32_e32 v31, v31
	v_pk_mul_f32 v[32:33], v[32:33], v[0:1] op_sel_hi:[1,0]
	v_pk_mul_f32 v[26:27], v[26:27], v[0:1] op_sel_hi:[1,0]
	v_pk_mul_f32 v[32:33], v[4:5], v[32:33]
	v_pk_add_f32 v[38:39], v[30:31], 1.0 op_sel_hi:[1,0]
	v_lshl_add_u64 v[30:31], v[116:117], 0, v[36:37]
	v_pk_mul_f32 v[26:27], v[6:7], v[26:27]
	v_pk_mul_f32 v[28:29], v[28:29], v[0:1] op_sel_hi:[1,0]
	v_pk_mul_f32 v[22:23], v[22:23], v[0:1] op_sel_hi:[1,0]
	v_rcp_f32_e32 v36, v39
	s_nop 0
	v_mul_f32_e32 v39, v35, v36
	v_mul_f32_e32 v36, 0xbfb8aa3b, v32
	v_mul_f32_e32 v37, 0xbfb8aa3b, v33
	v_exp_f32_e32 v36, v36
	v_exp_f32_e32 v37, v37
	s_nop 0
	v_pk_add_f32 v[36:37], v[36:37], 1.0 op_sel_hi:[1,0]
	v_rcp_f32_e32 v35, v38
	s_nop 0
	v_mul_f32_e32 v38, v34, v35
	v_pk_mul_f32 v[28:29], v[8:9], v[28:29]
	v_rcp_f32_e32 v34, v37
	s_nop 0
	v_mul_f32_e32 v33, v33, v34
	v_pk_mul_f32 v[22:23], v[10:11], v[22:23]
	v_mul_f32_e32 v34, 0xbfb8aa3b, v26
	v_mul_f32_e32 v35, 0xbfb8aa3b, v27
	v_exp_f32_e32 v34, v34
	v_exp_f32_e32 v35, v35
	v_rcp_f32_e32 v37, v36
	s_nop 0
	v_mul_f32_e32 v36, v32, v37
	v_cvt_pk_bf16_f32 v33, v36, v33
	v_cvt_pk_bf16_f32 v32, v38, v39
	v_pk_add_f32 v[34:35], v[34:35], 1.0 op_sel_hi:[1,0]
	global_store_dwordx2 v[30:31], v[32:33], off
	v_pk_mul_f32 v[24:25], v[24:25], v[0:1] op_sel_hi:[1,0]
	v_pk_mul_f32 v[18:19], v[18:19], v[0:1] op_sel_hi:[1,0]
	v_pk_mul_f32 v[24:25], v[12:13], v[24:25]
	v_rcp_f32_e32 v32, v35
	s_nop 0
	v_mul_f32_e32 v35, v27, v32
	v_mul_f32_e32 v32, 0xbfb8aa3b, v28
	v_mul_f32_e32 v33, 0xbfb8aa3b, v29
	v_exp_f32_e32 v32, v32
	v_exp_f32_e32 v33, v33
	s_nop 0
	v_pk_add_f32 v[32:33], v[32:33], 1.0 op_sel_hi:[1,0]
	v_rcp_f32_e32 v27, v34
	s_nop 0
	v_mul_f32_e32 v34, v26, v27
	v_pk_mul_f32 v[18:19], v[14:15], v[18:19]
	v_rcp_f32_e32 v26, v33
	s_nop 0
	v_mul_f32_e32 v29, v29, v26
	v_pk_mul_f32 v[20:21], v[20:21], v[0:1] op_sel_hi:[1,0]
	v_mul_f32_e32 v26, 0xbfb8aa3b, v22
	v_mul_f32_e32 v27, 0xbfb8aa3b, v23
	v_exp_f32_e32 v26, v26
	v_exp_f32_e32 v27, v27
	v_rcp_f32_e32 v33, v32
	s_nop 0
	v_mul_f32_e32 v32, v28, v33
	v_cvt_pk_bf16_f32 v29, v32, v29
	v_cvt_pk_bf16_f32 v28, v34, v35
	v_pk_add_f32 v[26:27], v[26:27], 1.0 op_sel_hi:[1,0]
	global_store_dwordx2 v[30:31], v[28:29], off offset:512
	v_pk_mul_f32 v[20:21], v[16:17], v[20:21]
	v_rcp_f32_e32 v28, v27
	s_nop 0
	v_mul_f32_e32 v27, v23, v28
	v_mul_f32_e32 v28, 0xbfb8aa3b, v24
	v_mul_f32_e32 v29, 0xbfb8aa3b, v25
	v_exp_f32_e32 v28, v28
	v_exp_f32_e32 v29, v29
	s_nop 0
	v_pk_add_f32 v[28:29], v[28:29], 1.0 op_sel_hi:[1,0]
	v_rcp_f32_e32 v23, v26
	s_nop 0
	v_mul_f32_e32 v26, v22, v23
	v_rcp_f32_e32 v22, v29
	s_nop 0
	v_mul_f32_e32 v25, v25, v22
	v_mul_f32_e32 v22, 0xbfb8aa3b, v18
	v_mul_f32_e32 v23, 0xbfb8aa3b, v19
	v_exp_f32_e32 v22, v22
	v_exp_f32_e32 v23, v23
	v_rcp_f32_e32 v29, v28
	s_nop 0
	v_mul_f32_e32 v28, v24, v29
	v_cvt_pk_bf16_f32 v24, v26, v27
	v_cvt_pk_bf16_f32 v25, v28, v25
	v_pk_add_f32 v[22:23], v[22:23], 1.0 op_sel_hi:[1,0]
	global_store_dwordx2 v[30:31], v[24:25], off offset:1024
	s_nop 0
	v_mul_f32_e32 v24, 0xbfb8aa3b, v20
	v_mul_f32_e32 v25, 0xbfb8aa3b, v21
	v_rcp_f32_e32 v0, v23
	s_nop 0
	v_mul_f32_e32 v0, v19, v0
	v_exp_f32_e32 v24, v24
	v_exp_f32_e32 v25, v25
	s_nop 0
	v_pk_add_f32 v[24:25], v[24:25], 1.0 op_sel_hi:[1,0]
	v_rcp_f32_e32 v19, v22
	s_nop 0
	v_mul_f32_e32 v18, v18, v19
	v_cvt_pk_bf16_f32 v18, v18, v0
	v_rcp_f32_e32 v19, v25
	s_nop 0
	v_mul_f32_e32 v19, v21, v19
	v_readlane_b32 s0, v254, 23
	v_rcp_f32_e32 v21, v24
	s_nop 0
	v_mul_f32_e32 v20, v20, v21
	v_cvt_pk_bf16_f32 v19, v20, v19
	s_cmp_ge_i32 s94, s0
	global_store_dwordx2 v[30:31], v[18:19], off offset:1536
	s_barrier
	s_cbranch_scc0 .LBB0_501
	v_readlane_b32 s96, v253, 54
	v_readlane_b32 s18, v253, 51
	v_readlane_b32 s76, v255, 7
	v_readlane_b32 s88, v253, 53
	v_readlane_b32 s97, v253, 55
	v_readlane_b32 s69, v253, 56
	v_readlane_b32 s72, v253, 57
	v_readlane_b32 s74, v253, 59
	s_movk_i32 s71, 0x200
	v_readlane_b32 s75, v253, 60
	v_readlane_b32 s78, v253, 61
	v_readlane_b32 s79, v253, 62
	v_readlane_b32 s80, v253, 63
	v_readlane_b32 s81, v254, 0
	v_readlane_b32 s82, v254, 1
	v_readlane_b32 s83, v254, 2
	s_movk_i32 s85, 0x400
	s_movk_i32 s87, 0x3000
	v_readlane_b32 s89, v254, 3
	v_readlane_b32 s48, v253, 49
	s_movk_i32 s49, 0x3fff
	s_movk_i32 s51, 0x40ff
	s_mov_b32 s52, 0x2aaaaaab
	s_movk_i32 s53, 0x80
	s_movk_i32 s54, 0x7ff
	s_movk_i32 s55, 0xfff
	s_movk_i32 s56, 0x3ff
	s_movk_i32 s57, 0xfa00
	s_movk_i32 s58, 0x1800
	s_movk_i32 s59, 0x500
	s_movk_i32 s60, 0xff00
	s_movk_i32 s61, 0x2ff
	s_movk_i32 s62, 0x1ff
	s_movk_i32 s63, 0x67
	s_movk_i32 s64, 0x6f
	s_movk_i32 s27, 0x77
	s_movk_i32 s29, 0x7f
	v_readlane_b32 s30, v253, 50
	s_mov_b32 s31, 0x3f2aaaab
	s_mov_b32 s43, 0x3f317218
	s_mov_b32 s44, 0x7f800000
	s_mov_b32 s45, 0x33800000
	s_movk_i32 s47, 0x210
	s_movk_i32 s46, 0x1000
	s_mov_b32 s65, 0x16900000
	s_movk_i32 s66, 0x110
	s_movk_i32 s28, 0x2000
	s_mov_b32 s34, 0x2e8ba2e9
	s_movk_i32 s35, 0xea00
	s_movk_i32 s36, 0xd400
	s_movk_i32 s37, 0xaff
	s_mov_b32 s38, 0x7fffea10
	s_mov_b32 s39, 0x7fffea20
	s_mov_b32 s40, 0x7fffea30
	s_mov_b32 s41, 0xffd40000
	s_movk_i32 s42, 0x57f
	v_readlane_b32 s19, v253, 52
	v_readlane_b32 s25, v254, 63
	v_readlane_b32 s26, v255, 9
	v_readlane_b32 s77, v255, 8
	v_readlane_b32 s68, v255, 6
	v_readlane_b32 s73, v253, 58
